# v033sink
# baseline (speedup 1.0000x reference)
; DEV int opaque_tid512() { int t = threadIdx.x; asm volatile("" : "+v"(t)); return t; }
;   #define STAGE(P,BASE,LD,br,kt) do{ const HALF* _u=(BASE)+(long)(br)*(((&(LD))==&lda)?lda_u:(LD))+(long)(kt)*G_BK; \
;     for(int _i=0;_i<2;++_i){ \
;       __builtin_amdgcn_global_load_lds((const unsigned*)(_u+(long)_i*(((&(LD))==&lda)?stepa:stepb)+((&(LD))==&lda?oa0:ob0)), \
;         (unsigned*)((char*)(P)+t5*16+_i*8192),16,0,0);}}while(0)
;   #define BAR __builtin_amdgcn_s_barrier()
;     ...
;   const int t5=opaque_tid512();
;   const int wid=t5>>6,lane=t5&63,wr=wid>>2,wc=wid&3,fr=lane&15,fq=lane>>4;
;   h8 At[4][2],B0[2][2],B1[2][2];
;   const int nt=K/G_BK;
;   const int _ob=fr*64+fq*16, _sw=_ob^(((_ob>>9)&1)<<5);
;   const char* la=(const char*)shm+wr*8192+_sw;
;   const char* lb=(const char*)shm+65536+wc*4096+_sw;
;   unsigned oa0, ob0;
;   const int stepa = n2 ? 1024 : 64 * lda, stepb = 64 * ldb;
;   const int lda_u = n2 ? 16 : lda;
;   {int _b=t5*16;int _r,_c;g_stage_rc(_b,_r,_c);
;     oa0=n2 ? (unsigned)((n2*(_r&63)+(_r>>6))*1024+_c) : (unsigned)(_r*lda+_c); ob0=(unsigned)(_r*ldb+_c);}
;   STAGE(SB(0,0),Bt,ldb,0,0); STAGE(SA(0,0),A,lda,0,0);
;   STAGE(SB(0,1),Bt,ldb,G_HALF,0); STAGE(SA(0,1),A,lda,G_HALF,0);
;   if(wr==1)BAR;
; __device__ void job_merged_g(const P& p, int g, int job, const HALF* GTbuf, HALF* sm) {
;     ...
;   zero_acc256(acc);
;   asm volatile("s_waitcnt vmcnt(0)" ::: "memory");
;   __syncthreads();
;   gemm256(acc, FM, 1024, Wfo, 1024, 1024, sm);
.LBB0_124:
	v_mov_b32_e32 v130, v155
	s_mov_b64 s[0:1], s[4:5]
	v_mov_b32_e32 v131, v155
	v_ashrrev_i32_e32 v0, 31, v131
	v_lshrrev_b32_e32 v0, 26, v0
	v_add_u32_e32 v0, v131, v0
	v_ashrrev_i32_e32 v4, 6, v0
	v_bfe_i32 v0, v131, 27, 1
	v_lshlrev_b32_e32 v5, 4, v131
	v_lshrrev_b32_e32 v0, 22, v0
	v_add_u32_e32 v0, v5, v0
	s_lshl_b32 s2, s22, 6
	s_and_b32 s2, s2, 0xfffff800
	s_lshl_b32 s58, s22, 8
	s_and_b32 s58, s58, 0x700
	s_or_b32 s58, s58, s2
	v_and_b32_e32 v0, 0xfffffc00, v0
	s_ashr_i32 s59, s58, 31
	v_sub_u32_e32 v0, v5, v0
	s_lshl_b64 s[2:3], s[58:59], 11
	v_lshrrev_b32_e32 v1, 4, v0
	s_add_u32 s2, s0, s2
	v_bitop3_b32 v1, v1, v0, 32 bitop3:0x6c
	v_ashrrev_i32_e32 v0, 31, v0
	s_addc_u32 s3, s1, s3
	v_lshrrev_b32_e32 v0, 26, v0
	s_add_u32 s2, s2, 0x29eb0000
	v_lshlrev_b32_e32 v2, 3, v4
	v_add_u32_e32 v0, v1, v0
	s_addc_u32 s3, s3, 0
	s_lshl_b32 s4, s22, 5
	v_and_b32_e32 v2, 0x3ffff0, v2
	v_ashrrev_i32_e32 v6, 6, v0
	s_and_b32 s80, s4, 0x300
	v_add_u32_e32 v0, v6, v2
	v_lshlrev_b32_e32 v2, 5, v4
	s_lshl_b32 s23, s80, 10
	s_lshl_b32 s4, s80, 11
	v_and_b32_e32 v7, 32, v2
	v_mul_i32_i24_e32 v2, 64, v6
	s_add_u32 s4, s0, s4
	v_sub_u32_e32 v1, v1, v2
	s_addc_u32 s5, s1, 0
	v_ashrrev_i16_sdwa v8, v174, sext(v1) dst_sel:DWORD dst_unused:UNUSED_PAD src0_sel:DWORD src1_sel:BYTE_0
	v_lshl_or_b32 v0, v0, 10, v7
	s_add_u32 s4, s4, 0x1c00000
	v_add_u32_sdwa v152, v0, sext(v8) dst_sel:DWORD dst_unused:UNUSED_PAD src0_sel:DWORD src1_sel:WORD_0
	v_add_u32_e32 v134, s95, v5
	s_addc_u32 s5, s5, 0
	v_lshlrev_b64 v[2:3], 1, v[152:153]
	v_readfirstlane_b32 s6, v134
	v_add_u32_e32 v135, 0x2000, v134
	v_lshl_add_u64 v[0:1], s[4:5], 0, v[2:3]
	s_mov_b32 m0, s6
	s_mov_b64 s[8:9], 0x20000
	v_readfirstlane_b32 s6, v135
	v_add_u32_e32 v136, 0, v5
	s_waitcnt vmcnt(0)
	s_barrier
	global_load_lds_dwordx4 v[0:1], off
	v_lshl_add_u64 v[10:11], v[0:1], 0, s[8:9]
	s_mov_b32 m0, s6
	v_readfirstlane_b32 s6, v136
	v_add_u32_e32 v137, 0x2000, v136
	global_load_lds_dwordx4 v[10:11], off
	v_lshl_add_u64 v[2:3], s[2:3], 0, v[2:3]
	s_mov_b32 m0, s6
	v_readfirstlane_b32 s6, v137
	v_add_u32_e32 v138, s28, v5
	global_load_lds_dwordx4 v[2:3], off
	v_lshl_add_u64 v[10:11], v[2:3], 0, s[8:9]
	s_mov_b32 m0, s6
	s_mov_b64 s[8:9], 0x40000
	v_readfirstlane_b32 s6, v138
	v_add_u32_e32 v139, 0x2000, v138
	global_load_lds_dwordx4 v[10:11], off
	v_lshl_add_u64 v[10:11], v[0:1], 0, s[8:9]
	s_mov_b32 m0, s6
	s_mov_b64 s[10:11], 0x60000
	v_readfirstlane_b32 s6, v139
	v_add_u32_e32 v140, 0x4000, v136
	global_load_lds_dwordx4 v[10:11], off
	v_lshl_add_u64 v[10:11], v[0:1], 0, s[10:11]
	s_mov_b32 m0, s6
	v_readfirstlane_b32 s6, v140
	v_add_u32_e32 v141, 0x6000, v136
	global_load_lds_dwordx4 v[10:11], off
	v_lshl_add_u64 v[10:11], v[2:3], 0, s[8:9]
	s_mov_b32 m0, s6
	v_readfirstlane_b32 s6, v141
	global_load_lds_dwordx4 v[10:11], off
	v_lshl_add_u64 v[10:11], v[2:3], 0, s[10:11]
	s_mov_b32 m0, s6
	v_ashrrev_i32_e32 v9, 8, v131
	global_load_lds_dwordx4 v[10:11], off
	v_cmp_eq_u32_e32 vcc, 1, v9
	s_and_saveexec_b64 s[6:7], vcc
	s_cbranch_execz .LBB0_126
	s_barrier

; DEV int opaque_tid512() { int t = threadIdx.x; asm volatile("" : "+v"(t)); return t; }
;   #define STAGE(P,BASE,LD,br,kt) do{ const HALF* _u=(BASE)+(long)(br)*(((&(LD))==&lda)?lda_u:(LD))+(long)(kt)*G_BK; \
;     for(int _i=0;_i<2;++_i){ \
;       __builtin_amdgcn_global_load_lds((const unsigned*)(_u+(long)_i*(((&(LD))==&lda)?stepa:stepb)+((&(LD))==&lda?oa0:ob0)), \
;         (unsigned*)((char*)(P)+t5*16+_i*8192),16,0,0);}}while(0)
;   #define BAR __builtin_amdgcn_s_barrier()
;     ...
;   const int t5=opaque_tid512();
;   const int wid=t5>>6,lane=t5&63,wr=wid>>2,wc=wid&3,fr=lane&15,fq=lane>>4;
;   h8 At[4][2],B0[2][2],B1[2][2];
;   const int nt=K/G_BK;
;   const int _ob=fr*64+fq*16, _sw=_ob^(((_ob>>9)&1)<<5);
;   const char* la=(const char*)shm+wr*8192+_sw;
;   const char* lb=(const char*)shm+65536+wc*4096+_sw;
;   unsigned oa0, ob0;
;   const int stepa = n2 ? 1024 : 64 * lda, stepb = 64 * ldb;
;   const int lda_u = n2 ? 16 : lda;
;   {int _b=t5*16;int _r,_c;g_stage_rc(_b,_r,_c);
;     oa0=n2 ? (unsigned)((n2*(_r&63)+(_r>>6))*1024+_c) : (unsigned)(_r*lda+_c); ob0=(unsigned)(_r*ldb+_c);}
;   STAGE(SB(0,0),Bt,ldb,0,0); STAGE(SA(0,0),A,lda,0,0);
;   STAGE(SB(0,1),Bt,ldb,G_HALF,0); STAGE(SA(0,1),A,lda,G_HALF,0);
;   if(wr==1)BAR;
; __device__ void job_merged_g(const P& p, int g, int job, const HALF* GTbuf, HALF* sm) {
;     ...
;   zero_acc256(acc);
;   asm volatile("s_waitcnt vmcnt(0)" ::: "memory");
;   __syncthreads();
;   gemm256(acc, RO, 2048, Wro, 2048, 2048, sm);
.LBB0_136:
	s_or_b64 exec, exec, s[12:13]
	v_mov_b32_e32 v133, v155
	s_lshl_b64 s[12:13], s[58:59], 12
	v_ashrrev_i32_e32 v0, 31, v133
	v_lshrrev_b32_e32 v0, 26, v0
	v_add_u32_e32 v0, v133, v0
	v_ashrrev_i32_e32 v4, 6, v0
	v_bfe_i32 v0, v133, 27, 1
	v_lshlrev_b32_e32 v5, 4, v133
	v_lshrrev_b32_e32 v0, 22, v0
	v_add_u32_e32 v0, v5, v0
	v_and_b32_e32 v0, 0xfffffc00, v0
	v_sub_u32_e32 v0, v5, v0
	v_lshrrev_b32_e32 v1, 4, v0
	v_bitop3_b32 v1, v1, v0, 32 bitop3:0x6c
	v_ashrrev_i32_e32 v0, 31, v0
	v_lshrrev_b32_e32 v0, 26, v0
	s_add_u32 s12, s0, s12
	v_lshlrev_b32_e32 v2, 3, v4
	v_add_u32_e32 v0, v1, v0
	s_addc_u32 s13, s1, s13
	v_and_b32_e32 v2, 0x1ffff0, v2
	v_ashrrev_i32_e32 v6, 6, v0
	s_add_u32 s58, s12, 0x2feb0000
	v_add_u32_e32 v0, v6, v2
	v_lshlrev_b32_e32 v2, 5, v4
	s_addc_u32 s59, s13, 0
	s_lshl_b32 s12, s80, 12
	v_and_b32_e32 v7, 32, v2
	v_mul_i32_i24_e32 v2, 64, v6
	s_add_u32 s12, s0, s12
	v_sub_u32_e32 v1, v1, v2
	s_addc_u32 s13, s1, 0
	v_ashrrev_i16_sdwa v8, v174, sext(v1) dst_sel:DWORD dst_unused:UNUSED_PAD src0_sel:DWORD src1_sel:BYTE_0
	v_lshl_or_b32 v0, v0, 11, v7
	s_add_u32 s12, s12, 0x1e00000
	v_add_u32_sdwa v152, v0, sext(v8) dst_sel:DWORD dst_unused:UNUSED_PAD src0_sel:DWORD src1_sel:WORD_0
	v_add_u32_e32 v136, s95, v5
	s_addc_u32 s13, s13, 0
	v_lshlrev_b64 v[2:3], 1, v[152:153]
	v_readfirstlane_b32 s14, v136
	v_add_u32_e32 v137, 0x2000, v136
	v_lshl_add_u64 v[0:1], s[12:13], 0, v[2:3]
	s_mov_b32 m0, s14
	s_mov_b64 s[68:69], 0x40000
	v_readfirstlane_b32 s14, v137
	v_add_u32_e32 v138, 0, v5
	s_waitcnt vmcnt(0)
	s_waitcnt lgkmcnt(0)
	s_barrier
	global_load_lds_dwordx4 v[0:1], off
	v_lshl_add_u64 v[10:11], v[0:1], 0, s[68:69]
	s_mov_b32 m0, s14
	v_readfirstlane_b32 s14, v138
	v_add_u32_e32 v139, 0x2000, v138
	global_load_lds_dwordx4 v[10:11], off
	v_lshl_add_u64 v[2:3], s[58:59], 0, v[2:3]
	s_mov_b32 m0, s14
	v_readfirstlane_b32 s14, v139
	v_add_u32_e32 v140, s28, v5
	global_load_lds_dwordx4 v[2:3], off
	v_lshl_add_u64 v[10:11], v[2:3], 0, s[68:69]
	s_mov_b32 m0, s14
	s_mov_b64 s[68:69], 0x80000
	v_readfirstlane_b32 s14, v140
	v_add_u32_e32 v141, 0x2000, v140
	global_load_lds_dwordx4 v[10:11], off
	v_lshl_add_u64 v[10:11], v[0:1], 0, s[68:69]
	s_mov_b32 m0, s14
	s_mov_b64 s[72:73], 0xc0000
	v_readfirstlane_b32 s14, v141
	v_add_u32_e32 v142, 0x4000, v138
	global_load_lds_dwordx4 v[10:11], off
	v_lshl_add_u64 v[10:11], v[0:1], 0, s[72:73]
	s_mov_b32 m0, s14
	v_readfirstlane_b32 s14, v142
	v_add_u32_e32 v143, 0x6000, v138
	global_load_lds_dwordx4 v[10:11], off
	v_lshl_add_u64 v[10:11], v[2:3], 0, s[68:69]
	s_mov_b32 m0, s14
	v_readfirstlane_b32 s14, v143
	global_load_lds_dwordx4 v[10:11], off
	v_lshl_add_u64 v[10:11], v[2:3], 0, s[72:73]
	s_mov_b32 m0, s14
	v_ashrrev_i32_e32 v9, 8, v133
	global_load_lds_dwordx4 v[10:11], off
	v_cmp_eq_u32_e32 vcc, 1, v9
	s_and_saveexec_b64 s[14:15], vcc
	s_cbranch_execz .LBB0_138
	s_barrier

; DEV int opaque_tid512() { int t = threadIdx.x; asm volatile("" : "+v"(t)); return t; }
;   #define STAGE(P,BASE,LD,br,kt) do{ const HALF* _u=(BASE)+(long)(br)*(((&(LD))==&lda)?lda_u:(LD))+(long)(kt)*G_BK; \
;     for(int _i=0;_i<2;++_i){ \
;       __builtin_amdgcn_global_load_lds((const unsigned*)(_u+(long)_i*(((&(LD))==&lda)?stepa:stepb)+((&(LD))==&lda?oa0:ob0)), \
;         (unsigned*)((char*)(P)+t5*16+_i*8192),16,0,0);}}while(0)
;   #define BAR __builtin_amdgcn_s_barrier()
;     ...
;   const int t5=opaque_tid512();
;   const int wid=t5>>6,lane=t5&63,wr=wid>>2,wc=wid&3,fr=lane&15,fq=lane>>4;
;   h8 At[4][2],B0[2][2],B1[2][2];
;   const int nt=K/G_BK;
;   const int _ob=fr*64+fq*16, _sw=_ob^(((_ob>>9)&1)<<5);
;   const char* la=(const char*)shm+wr*8192+_sw;
;   const char* lb=(const char*)shm+65536+wc*4096+_sw;
;   unsigned oa0, ob0;
;   const int stepa = n2 ? 1024 : 64 * lda, stepb = 64 * ldb;
;   const int lda_u = n2 ? 16 : lda;
;   {int _b=t5*16;int _r,_c;g_stage_rc(_b,_r,_c);
;     oa0=n2 ? (unsigned)((n2*(_r&63)+(_r>>6))*1024+_c) : (unsigned)(_r*lda+_c); ob0=(unsigned)(_r*ldb+_c);}
;   STAGE(SB(0,0),Bt,ldb,0,0); STAGE(SA(0,0),A,lda,0,0);
;   STAGE(SB(0,1),Bt,ldb,G_HALF,0); STAGE(SA(0,1),A,lda,G_HALF,0);
;   if(wr==1)BAR;
; __device__ void job_merged_g(const P& p, int g, int job, const HALF* GTbuf, HALF* sm) {
;     ...
;   zero_acc256(acc);
;   asm volatile("s_waitcnt vmcnt(0)" ::: "memory");
;   __syncthreads();
;   gemm256(acc, CY, 1024, Wco, 1024, 1024, sm);
.LBB0_148:
	s_or_b64 exec, exec, s[12:13]
	v_mov_b32_e32 v133, v155
	s_lshl_b64 s[12:13], s[70:71], 1
	v_ashrrev_i32_e32 v0, 31, v133
	v_lshrrev_b32_e32 v0, 26, v0
	v_add_u32_e32 v0, v133, v0
	v_ashrrev_i32_e32 v4, 6, v0
	v_bfe_i32 v0, v133, 27, 1
	v_lshlrev_b32_e32 v5, 4, v133
	v_lshrrev_b32_e32 v0, 22, v0
	v_add_u32_e32 v0, v5, v0
	v_and_b32_e32 v0, 0xfffffc00, v0
	v_sub_u32_e32 v0, v5, v0
	v_lshrrev_b32_e32 v1, 4, v0
	v_bitop3_b32 v1, v1, v0, 32 bitop3:0x6c
	v_ashrrev_i32_e32 v0, 31, v0
	v_lshrrev_b32_e32 v0, 26, v0
	s_add_u32 s12, s0, s12
	v_lshlrev_b32_e32 v2, 3, v4
	v_add_u32_e32 v0, v1, v0
	s_addc_u32 s13, s1, s13
	v_and_b32_e32 v2, 0x3ffff0, v2
	v_ashrrev_i32_e32 v6, 6, v0
	s_add_u32 s58, s12, 0x31eb0000
	v_add_u32_e32 v0, v6, v2
	v_lshlrev_b32_e32 v2, 5, v4
	s_addc_u32 s59, s13, 0
	s_lshl_b32 s12, s23, 1
	v_and_b32_e32 v7, 32, v2
	v_mul_i32_i24_e32 v2, 64, v6
	s_add_u32 s0, s0, s12
	v_sub_u32_e32 v1, v1, v2
	s_addc_u32 s1, s1, 0
	v_ashrrev_i16_sdwa v8, v174, sext(v1) dst_sel:DWORD dst_unused:UNUSED_PAD src0_sel:DWORD src1_sel:BYTE_0
	v_lshl_or_b32 v0, v0, 10, v7
	s_add_u32 s0, s0, 0x2200000
	v_add_u32_sdwa v152, v0, sext(v8) dst_sel:DWORD dst_unused:UNUSED_PAD src0_sel:DWORD src1_sel:WORD_0
	v_add_u32_e32 v136, s95, v5
	s_addc_u32 s1, s1, 0
	v_lshlrev_b64 v[2:3], 1, v[152:153]
	v_readfirstlane_b32 s12, v136
	v_add_u32_e32 v137, 0x2000, v136
	v_lshl_add_u64 v[0:1], s[0:1], 0, v[2:3]
	s_mov_b32 m0, s12
	s_mov_b64 s[14:15], 0x20000
	v_readfirstlane_b32 s12, v137
	v_add_u32_e32 v138, 0, v5
	s_waitcnt vmcnt(0)
	s_waitcnt lgkmcnt(0)
	s_barrier
	global_load_lds_dwordx4 v[0:1], off
	v_lshl_add_u64 v[10:11], v[0:1], 0, s[14:15]
	s_mov_b32 m0, s12
	v_readfirstlane_b32 s12, v138
	v_add_u32_e32 v139, 0x2000, v138
	global_load_lds_dwordx4 v[10:11], off
	v_lshl_add_u64 v[2:3], s[58:59], 0, v[2:3]
	s_mov_b32 m0, s12
	v_readfirstlane_b32 s12, v139
	v_add_u32_e32 v140, s28, v5
	global_load_lds_dwordx4 v[2:3], off
	v_lshl_add_u64 v[10:11], v[2:3], 0, s[14:15]
	s_mov_b32 m0, s12
	s_mov_b64 s[14:15], 0x40000
	v_readfirstlane_b32 s12, v140
	v_add_u32_e32 v141, 0x2000, v140
	global_load_lds_dwordx4 v[10:11], off
	v_lshl_add_u64 v[10:11], v[0:1], 0, s[14:15]
	s_mov_b32 m0, s12
	s_mov_b64 s[68:69], 0x60000
	v_readfirstlane_b32 s12, v141
	v_add_u32_e32 v142, 0x4000, v138
	global_load_lds_dwordx4 v[10:11], off
	v_lshl_add_u64 v[10:11], v[0:1], 0, s[68:69]
	s_mov_b32 m0, s12
	v_readfirstlane_b32 s12, v142
	v_add_u32_e32 v143, 0x6000, v138
	global_load_lds_dwordx4 v[10:11], off
	v_lshl_add_u64 v[10:11], v[2:3], 0, s[14:15]
	s_mov_b32 m0, s12
	v_readfirstlane_b32 s12, v143
	global_load_lds_dwordx4 v[10:11], off
	v_lshl_add_u64 v[10:11], v[2:3], 0, s[68:69]
	s_mov_b32 m0, s12
	v_ashrrev_i32_e32 v9, 8, v133
	global_load_lds_dwordx4 v[10:11], off
	v_cmp_eq_u32_e32 vcc, 1, v9
	s_and_saveexec_b64 s[12:13], vcc
	s_cbranch_execz .LBB0_150
	s_barrier

; DEV int opaque_tid512() { int t = threadIdx.x; asm volatile("" : "+v"(t)); return t; }
;   #define STAGE(P,BASE,LD,br,kt) do{ const HALF* _u=(BASE)+(long)(br)*(((&(LD))==&lda)?lda_u:(LD))+(long)(kt)*G_BK; \
;     for(int _i=0;_i<2;++_i){ \
;       __builtin_amdgcn_global_load_lds((const unsigned*)(_u+(long)_i*(((&(LD))==&lda)?stepa:stepb)+((&(LD))==&lda?oa0:ob0)), \
;         (unsigned*)((char*)(P)+t5*16+_i*8192),16,0,0);}}while(0)
;   #define BAR __builtin_amdgcn_s_barrier()
;     ...
;   const int t5=opaque_tid512();
;   const int wid=t5>>6,lane=t5&63,wr=wid>>2,wc=wid&3,fr=lane&15,fq=lane>>4;
;   h8 At[4][2],B0[2][2],B1[2][2];
;   const int nt=K/G_BK;
;   const int _ob=fr*64+fq*16, _sw=_ob^(((_ob>>9)&1)<<5);
;   const char* la=(const char*)shm+wr*8192+_sw;
;   const char* lb=(const char*)shm+65536+wc*4096+_sw;
;   unsigned oa0, ob0;
;   const int stepa = n2 ? 1024 : 64 * lda, stepb = 64 * ldb;
;   const int lda_u = n2 ? 16 : lda;
;   {int _b=t5*16;int _r,_c;g_stage_rc(_b,_r,_c);
;     oa0=n2 ? (unsigned)((n2*(_r&63)+(_r>>6))*1024+_c) : (unsigned)(_r*lda+_c); ob0=(unsigned)(_r*ldb+_c);}
;   STAGE(SB(0,0),Bt,ldb,0,0); STAGE(SA(0,0),A,lda,0,0);
;   STAGE(SB(0,1),Bt,ldb,G_HALF,0); STAGE(SA(0,1),A,lda,G_HALF,0);
;   if(wr==1)BAR;
; __global__ void __launch_bounds__(512, 2) mega(P p) {
;     ...
;           const int ct2 = 55 - (j >> 5), rt = j & 31;
;           if (ct2 >= 44) job_gemm1_g<2, false>(p, g, ct2, rt, gt_cur, 3072, (ct2 - 44) * 256, sm);
;           else if (ct2 >= 32) job_gemm1_g<0, false>(p, g, ct2, rt, (HALF*)(ws + G_CV), 3072, (ct2 - 32) * 256, sm);
;           else if (ct2 >= 24) job_gemm1_g<1, false>(p, g, ct2, rt, (HALF*)(ws + G_G), 2048, (ct2 - 24) * 256, sm);
;           else if (ct2 >= 16) job_gemm1_g<0, true>(p, g, ct2, rt, (HALF*)(ws + G_VT), 8192, (ct2 - 16) * 256, sm);
;           else if (ct2 >= 12) job_qk_g<true>(p, l, g, ct2, rt, sm);
;           else if (ct2 >= 8) job_qk_g<false>(p, l, g, ct2, rt, sm);
;           else job_fourier_g(p, g, ct2, rt, sm);
.LBB0_169:
	s_cmp_gt_u32 s23, 23
	s_cbranch_scc0 .LBB0_275
	s_cmp_gt_u32 s23, 31
	s_cbranch_scc0 .LBB0_258
	s_cmp_gt_u32 s23, 39
	s_cbranch_scc0 .LBB0_241
	s_cmp_gt_u32 s23, 43
	s_cbranch_scc0 .LBB0_205
	s_cmp_gt_u32 s23, 47
	s_cbranch_scc0 .LBB0_189
	v_readlane_b32 s68, v255, 39
	v_readlane_b32 s72, v255, 43
	v_readlane_b32 s73, v255, 44
	v_mov_b32_e32 v134, v155
	s_mov_b64 s[2:3], s[72:73]
	v_mov_b32_e32 v135, v155
	s_lshl_b32 s0, s9, 8
	v_ashrrev_i32_e32 v0, 31, v135
	v_lshrrev_b32_e32 v0, 26, v0
	v_add_u32_e32 v0, v135, v0
	v_readlane_b32 s1, v255, 60
	v_ashrrev_i32_e32 v2, 6, v0
	v_bfe_i32 v0, v135, 27, 1
	s_and_b32 s14, s0, s1
	v_readlane_b32 s1, v255, 61
	v_lshlrev_b32_e32 v3, 4, v135
	v_lshrrev_b32_e32 v0, 22, v0
	s_and_b32 s0, s0, s1
	v_add_u32_e32 v0, v3, v0
	s_lshr_b32 s15, s0, 6
	v_and_b32_e32 v0, 0xfffffc00, v0
	s_or_b32 s0, s14, s15
	v_sub_u32_e32 v0, v3, v0
	s_or_b32 s44, s0, s20
	v_lshrrev_b32_e32 v1, 4, v0
	s_lshl_b64 s[0:1], s[44:45], 11
	v_bitop3_b32 v1, v1, v0, 32 bitop3:0x6c
	v_ashrrev_i32_e32 v0, 31, v0
	s_add_u32 s0, s2, s0
	v_lshrrev_b32_e32 v0, 26, v0
	s_addc_u32 s1, s3, s1
	v_lshlrev_b32_e32 v4, 3, v2
	v_add_u32_e32 v0, v1, v0
	s_add_u32 s12, s0, 0x3eb0000
	v_and_b32_e32 v5, -16, v4
	v_ashrrev_i32_e32 v4, 6, v0
	s_addc_u32 s13, s1, 0
	s_lshl_b32 s0, s8, 8
	v_mul_i32_i24_e32 v6, 64, v4
	s_ashr_i32 s1, s0, 31
	v_add_u32_e32 v0, v4, v5
	v_lshlrev_b32_e32 v5, 5, v2
	v_sub_u32_e32 v1, v1, v6
	s_lshl_b64 s[6:7], s[0:1], 11
	v_and_b32_e32 v5, 32, v5
	v_ashrrev_i16_sdwa v6, v174, sext(v1) dst_sel:DWORD dst_unused:UNUSED_PAD src0_sel:DWORD src1_sel:BYTE_0
	s_add_u32 s58, s2, s6
	v_add_u32_sdwa v10, v5, sext(v6) dst_sel:DWORD dst_unused:UNUSED_PAD src0_sel:DWORD src1_sel:WORD_0
	v_and_b32_e32 v1, 63, v0
	v_lshrrev_b32_e32 v8, 6, v0
	v_readlane_b32 s1, v255, 62
	v_add_u32_e32 v138, s95, v3
	s_addc_u32 s59, s3, s7
	v_lshl_add_u32 v11, v1, s1, v8
	v_lshl_add_u32 v152, v0, 10, v10
	v_readfirstlane_b32 s1, v138
	v_add_u32_e32 v139, 0x2000, v138
	v_lshl_add_u64 v[0:1], v[152:153], 1, s[58:59]
	s_mov_b32 m0, s1
	s_mov_b64 s[58:59], 0x20000
	v_readfirstlane_b32 s1, v139
	v_add_u32_e32 v140, 0, v3
	s_waitcnt vmcnt(0)
	s_waitcnt lgkmcnt(0)
	s_barrier
	global_load_lds_dwordx4 v[0:1], off
	v_lshl_add_u64 v[8:9], v[0:1], 0, s[58:59]
	s_mov_b32 m0, s1
	v_lshl_add_u32 v152, v11, 10, v10
	v_readfirstlane_b32 s1, v140
	v_add_u32_e32 v141, 0x2000, v140
	global_load_lds_dwordx4 v[8:9], off
	v_lshl_add_u64 v[128:129], v[152:153], 1, s[12:13]
	s_mov_b32 m0, s1
	s_mov_b64 s[12:13], 0x800
	v_readfirstlane_b32 s1, v141
	v_add_u32_e32 v142, s28, v3
	global_load_lds_dwordx4 v[128:129], off
	v_lshl_add_u64 v[8:9], v[128:129], 0, s[12:13]
	s_mov_b32 m0, s1
	s_mov_b64 s[12:13], 0x40000
	v_readfirstlane_b32 s1, v142
	v_add_u32_e32 v143, 0x2000, v142
	global_load_lds_dwordx4 v[8:9], off
	v_lshl_add_u64 v[8:9], v[0:1], 0, s[12:13]
	s_mov_b32 m0, s1
	s_mov_b64 s[12:13], 0x60000
	v_readfirstlane_b32 s1, v143
	v_add_u32_e32 v144, 0x4000, v140
	global_load_lds_dwordx4 v[8:9], off
	v_lshl_add_u64 v[8:9], v[0:1], 0, s[12:13]
	s_mov_b32 m0, s1
	s_mov_b64 s[12:13], 0x1000
	v_readfirstlane_b32 s1, v144
	v_add_u32_e32 v145, 0x6000, v140
	global_load_lds_dwordx4 v[8:9], off
	v_lshl_add_u64 v[8:9], v[128:129], 0, s[12:13]
	s_mov_b32 m0, s1
	s_mov_b64 s[12:13], 0x1800
	v_readfirstlane_b32 s1, v145
	global_load_lds_dwordx4 v[8:9], off
	v_lshl_add_u64 v[8:9], v[128:129], 0, s[12:13]
	s_mov_b32 m0, s1
	v_ashrrev_i32_e32 v7, 8, v135
	global_load_lds_dwordx4 v[8:9], off
	v_cmp_eq_u32_e32 vcc, 1, v7
	v_readlane_b32 s69, v255, 40
	v_readlane_b32 s70, v255, 41
	v_readlane_b32 s71, v255, 42
	v_readlane_b32 s74, v255, 45
	v_readlane_b32 s75, v255, 46
	s_and_saveexec_b64 s[12:13], vcc
	s_cbranch_execz .LBB0_176
	s_barrier

; DEV int opaque_tid512() { int t = threadIdx.x; asm volatile("" : "+v"(t)); return t; }
;   #define STAGE(P,BASE,LD,br,kt) do{ const HALF* _u=(BASE)+(long)(br)*(((&(LD))==&lda)?lda_u:(LD))+(long)(kt)*G_BK; \
;     for(int _i=0;_i<2;++_i){ \
;       __builtin_amdgcn_global_load_lds((const unsigned*)(_u+(long)_i*(((&(LD))==&lda)?stepa:stepb)+((&(LD))==&lda?oa0:ob0)), \
;         (unsigned*)((char*)(P)+t5*16+_i*8192),16,0,0);}}while(0)
;   #define BAR __builtin_amdgcn_s_barrier()
;     ...
;   const int t5=opaque_tid512();
;   const int wid=t5>>6,lane=t5&63,wr=wid>>2,wc=wid&3,fr=lane&15,fq=lane>>4;
;   h8 At[4][2],B0[2][2],B1[2][2];
;   const int nt=K/G_BK;
;   const int _ob=fr*64+fq*16, _sw=_ob^(((_ob>>9)&1)<<5);
;   const char* la=(const char*)shm+wr*8192+_sw;
;   const char* lb=(const char*)shm+65536+wc*4096+_sw;
;   unsigned oa0, ob0;
;   const int stepa = n2 ? 1024 : 64 * lda, stepb = 64 * ldb;
;   const int lda_u = n2 ? 16 : lda;
;   {int _b=t5*16;int _r,_c;g_stage_rc(_b,_r,_c);
;     oa0=n2 ? (unsigned)((n2*(_r&63)+(_r>>6))*1024+_c) : (unsigned)(_r*lda+_c); ob0=(unsigned)(_r*ldb+_c);}
;   STAGE(SB(0,0),Bt,ldb,0,0); STAGE(SA(0,0),A,lda,0,0);
;   STAGE(SB(0,1),Bt,ldb,G_HALF,0); STAGE(SA(0,1),A,lda,G_HALF,0);
;   if(wr==1)BAR;
; template <bool ISK>
; __device__ void job_qk_g(const P& p, int l, int g, int ct2, int rt, HALF* sm) {
;     ...
;   const HALF* Ap = (const HALF*)(ws + OFF_X16) + (size_t)(g * GT_ + rt * 256) * 1024;
;   const HALF* Bp = (const HALF*)(ws + OFF_WIN) + (size_t)(ct2 * 256) * 1024;
;   f4 acc[2][2][4][2];
;   zero_acc256(acc);
;   asm volatile("s_waitcnt vmcnt(0)" ::: "memory");
;   __syncthreads();
;   gemm256(acc, Ap, 1024, Bp, 1024, 1024, sm);
.LBB0_189:
	s_and_b64 vcc, exec, s[0:1]
	s_cbranch_vccz .LBB0_306
	v_readlane_b32 s68, v255, 39
	v_readlane_b32 s72, v255, 43
	v_readlane_b32 s73, v255, 44
	v_mov_b32_e32 v130, v155
	s_mov_b64 s[0:1], s[72:73]
	v_mov_b32_e32 v131, v155
	s_lshl_b32 s21, s9, 8
	v_ashrrev_i32_e32 v0, 31, v131
	v_lshrrev_b32_e32 v0, 26, v0
	v_add_u32_e32 v0, v131, v0
	v_ashrrev_i32_e32 v4, 6, v0
	v_bfe_i32 v0, v131, 27, 1
	v_lshlrev_b32_e32 v5, 4, v131
	v_lshrrev_b32_e32 v0, 22, v0
	v_add_u32_e32 v0, v5, v0
	v_and_b32_e32 v0, 0xfffffc00, v0
	v_sub_u32_e32 v0, v5, v0
	v_lshrrev_b32_e32 v1, 4, v0
	v_bitop3_b32 v1, v1, v0, 32 bitop3:0x6c
	v_ashrrev_i32_e32 v0, 31, v0
	s_or_b32 s44, s21, s20
	v_lshrrev_b32_e32 v0, 26, v0
	s_lshl_b64 s[2:3], s[44:45], 11
	v_lshlrev_b32_e32 v2, 3, v4
	v_add_u32_e32 v0, v1, v0
	s_add_u32 s2, s0, s2
	v_and_b32_e32 v2, 0x3ffff0, v2
	v_ashrrev_i32_e32 v6, 6, v0
	s_addc_u32 s3, s1, s3
	v_add_u32_e32 v0, v6, v2
	v_lshlrev_b32_e32 v2, 5, v4
	s_add_u32 s2, s2, 0x3eb0000
	v_and_b32_e32 v7, 32, v2
	v_mul_i32_i24_e32 v2, 64, v6
	s_addc_u32 s3, s3, 0
	s_lshl_b32 s44, s8, 18
	v_sub_u32_e32 v1, v1, v2
	s_lshl_b64 s[6:7], s[44:45], 1
	v_ashrrev_i16_sdwa v8, v174, sext(v1) dst_sel:DWORD dst_unused:UNUSED_PAD src0_sel:DWORD src1_sel:BYTE_0
	v_lshl_or_b32 v0, v0, 10, v7
	s_add_u32 s12, s0, s6
	v_add_u32_sdwa v152, v0, sext(v8) dst_sel:DWORD dst_unused:UNUSED_PAD src0_sel:DWORD src1_sel:WORD_0
	v_add_u32_e32 v134, s95, v5
	s_addc_u32 s13, s1, s7
	v_lshlrev_b64 v[2:3], 1, v[152:153]
	v_readfirstlane_b32 s14, v134
	v_add_u32_e32 v135, 0x2000, v134
	v_lshl_add_u64 v[0:1], s[12:13], 0, v[2:3]
	s_mov_b32 m0, s14
	s_mov_b64 s[58:59], 0x20000
	v_readfirstlane_b32 s14, v135
	v_add_u32_e32 v136, 0, v5
	s_waitcnt vmcnt(0)
	s_waitcnt lgkmcnt(0)
	s_barrier
	global_load_lds_dwordx4 v[0:1], off
	v_lshl_add_u64 v[10:11], v[0:1], 0, s[58:59]
	s_mov_b32 m0, s14
	v_readfirstlane_b32 s14, v136
	v_add_u32_e32 v137, 0x2000, v136
	global_load_lds_dwordx4 v[10:11], off
	v_lshl_add_u64 v[2:3], s[2:3], 0, v[2:3]
	s_mov_b32 m0, s14
	v_readfirstlane_b32 s14, v137
	v_add_u32_e32 v138, s28, v5
	v_readlane_b32 s69, v255, 40
	global_load_lds_dwordx4 v[2:3], off
	v_lshl_add_u64 v[10:11], v[2:3], 0, s[58:59]
	s_mov_b32 m0, s14
	s_mov_b64 s[58:59], 0x40000
	v_readfirstlane_b32 s14, v138
	v_add_u32_e32 v139, 0x2000, v138
	global_load_lds_dwordx4 v[10:11], off
	v_lshl_add_u64 v[10:11], v[0:1], 0, s[58:59]
	s_mov_b32 m0, s14
	s_mov_b64 s[68:69], 0x60000
	v_readfirstlane_b32 s14, v139
	v_add_u32_e32 v140, 0x4000, v136
	global_load_lds_dwordx4 v[10:11], off
	v_lshl_add_u64 v[10:11], v[0:1], 0, s[68:69]
	s_mov_b32 m0, s14
	v_readfirstlane_b32 s14, v140
	v_add_u32_e32 v141, 0x6000, v136
	global_load_lds_dwordx4 v[10:11], off
	v_lshl_add_u64 v[10:11], v[2:3], 0, s[58:59]
	s_mov_b32 m0, s14
	v_readfirstlane_b32 s14, v141
	global_load_lds_dwordx4 v[10:11], off
	v_lshl_add_u64 v[10:11], v[2:3], 0, s[68:69]
	s_mov_b32 m0, s14
	v_ashrrev_i32_e32 v9, 8, v131
	global_load_lds_dwordx4 v[10:11], off
	v_cmp_eq_u32_e32 vcc, 1, v9
	v_readlane_b32 s70, v255, 41
	v_readlane_b32 s71, v255, 42
	v_readlane_b32 s74, v255, 45
	v_readlane_b32 s75, v255, 46
	s_and_saveexec_b64 s[14:15], vcc
	s_cbranch_execz .LBB0_192
	s_barrier

; DEV int opaque_tid512() { int t = threadIdx.x; asm volatile("" : "+v"(t)); return t; }
;   #define STAGE(P,BASE,LD,br,kt) do{ const HALF* _u=(BASE)+(long)(br)*(((&(LD))==&lda)?lda_u:(LD))+(long)(kt)*G_BK; \
;     for(int _i=0;_i<2;++_i){ \
;       __builtin_amdgcn_global_load_lds((const unsigned*)(_u+(long)_i*(((&(LD))==&lda)?stepa:stepb)+((&(LD))==&lda?oa0:ob0)), \
;         (unsigned*)((char*)(P)+t5*16+_i*8192),16,0,0);}}while(0)
;   #define BAR __builtin_amdgcn_s_barrier()
;     ...
;   const int t5=opaque_tid512();
;   const int wid=t5>>6,lane=t5&63,wr=wid>>2,wc=wid&3,fr=lane&15,fq=lane>>4;
;   h8 At[4][2],B0[2][2],B1[2][2];
;   const int nt=K/G_BK;
;   const int _ob=fr*64+fq*16, _sw=_ob^(((_ob>>9)&1)<<5);
;   const char* la=(const char*)shm+wr*8192+_sw;
;   const char* lb=(const char*)shm+65536+wc*4096+_sw;
;   unsigned oa0, ob0;
;   const int stepa = n2 ? 1024 : 64 * lda, stepb = 64 * ldb;
;   const int lda_u = n2 ? 16 : lda;
;   {int _b=t5*16;int _r,_c;g_stage_rc(_b,_r,_c);
;     oa0=n2 ? (unsigned)((n2*(_r&63)+(_r>>6))*1024+_c) : (unsigned)(_r*lda+_c); ob0=(unsigned)(_r*ldb+_c);}
;   STAGE(SB(0,0),Bt,ldb,0,0); STAGE(SA(0,0),A,lda,0,0);
;   STAGE(SB(0,1),Bt,ldb,G_HALF,0); STAGE(SA(0,1),A,lda,G_HALF,0);
;   if(wr==1)BAR;
; template <bool ISK>
; __device__ void job_qk_g(const P& p, int l, int g, int ct2, int rt, HALF* sm) {
;     ...
;   const HALF* Ap = (const HALF*)(ws + OFF_X16) + (size_t)(g * GT_ + rt * 256) * 1024;
;   const HALF* Bp = (const HALF*)(ws + OFF_WIN) + (size_t)(ct2 * 256) * 1024;
;   f4 acc[2][2][4][2];
;   zero_acc256(acc);
;   asm volatile("s_waitcnt vmcnt(0)" ::: "memory");
;   __syncthreads();
;   gemm256(acc, Ap, 1024, Bp, 1024, 1024, sm);
.LBB0_206:
	v_readlane_b32 s68, v255, 39
	v_readlane_b32 s72, v255, 43
	v_readlane_b32 s73, v255, 44
	v_mov_b32_e32 v130, v155
	s_mov_b64 s[0:1], s[72:73]
	v_mov_b32_e32 v131, v155
	s_lshl_b32 s21, s9, 8
	v_ashrrev_i32_e32 v0, 31, v131
	v_lshrrev_b32_e32 v0, 26, v0
	v_add_u32_e32 v0, v131, v0
	v_ashrrev_i32_e32 v4, 6, v0
	v_bfe_i32 v0, v131, 27, 1
	v_lshlrev_b32_e32 v5, 4, v131
	v_lshrrev_b32_e32 v0, 22, v0
	v_add_u32_e32 v0, v5, v0
	v_and_b32_e32 v0, 0xfffffc00, v0
	v_sub_u32_e32 v0, v5, v0
	v_lshrrev_b32_e32 v1, 4, v0
	v_bitop3_b32 v1, v1, v0, 32 bitop3:0x6c
	v_ashrrev_i32_e32 v0, 31, v0
	s_or_b32 s44, s21, s20
	v_lshrrev_b32_e32 v0, 26, v0
	s_lshl_b64 s[2:3], s[44:45], 11
	v_lshlrev_b32_e32 v2, 3, v4
	v_add_u32_e32 v0, v1, v0
	s_add_u32 s2, s0, s2
	v_and_b32_e32 v2, 0x3ffff0, v2
	v_ashrrev_i32_e32 v6, 6, v0
	s_addc_u32 s3, s1, s3
	v_add_u32_e32 v0, v6, v2
	v_lshlrev_b32_e32 v2, 5, v4
	s_add_u32 s2, s2, 0x3eb0000
	v_and_b32_e32 v7, 32, v2
	v_mul_i32_i24_e32 v2, 64, v6
	s_addc_u32 s3, s3, 0
	s_lshl_b32 s44, s8, 18
	v_sub_u32_e32 v1, v1, v2
	s_lshl_b64 s[6:7], s[44:45], 1
	v_ashrrev_i16_sdwa v8, v174, sext(v1) dst_sel:DWORD dst_unused:UNUSED_PAD src0_sel:DWORD src1_sel:BYTE_0
	v_lshl_or_b32 v0, v0, 10, v7
	s_add_u32 s12, s0, s6
	v_add_u32_sdwa v152, v0, sext(v8) dst_sel:DWORD dst_unused:UNUSED_PAD src0_sel:DWORD src1_sel:WORD_0
	v_add_u32_e32 v134, s95, v5
	s_addc_u32 s13, s1, s7
	v_lshlrev_b64 v[2:3], 1, v[152:153]
	v_readfirstlane_b32 s14, v134
	v_add_u32_e32 v135, 0x2000, v134
	v_lshl_add_u64 v[0:1], s[12:13], 0, v[2:3]
	s_mov_b32 m0, s14
	s_mov_b64 s[58:59], 0x20000
	v_readfirstlane_b32 s14, v135
	v_add_u32_e32 v136, 0, v5
	s_waitcnt vmcnt(0)
	s_waitcnt lgkmcnt(0)
	s_barrier
	global_load_lds_dwordx4 v[0:1], off
	v_lshl_add_u64 v[10:11], v[0:1], 0, s[58:59]
	s_mov_b32 m0, s14
	v_readfirstlane_b32 s14, v136
	v_add_u32_e32 v137, 0x2000, v136
	global_load_lds_dwordx4 v[10:11], off
	v_lshl_add_u64 v[2:3], s[2:3], 0, v[2:3]
	s_mov_b32 m0, s14
	v_readfirstlane_b32 s14, v137
	v_add_u32_e32 v138, s28, v5
	v_readlane_b32 s69, v255, 40
	global_load_lds_dwordx4 v[2:3], off
	v_lshl_add_u64 v[10:11], v[2:3], 0, s[58:59]
	s_mov_b32 m0, s14
	s_mov_b64 s[58:59], 0x40000
	v_readfirstlane_b32 s14, v138
	v_add_u32_e32 v139, 0x2000, v138
	global_load_lds_dwordx4 v[10:11], off
	v_lshl_add_u64 v[10:11], v[0:1], 0, s[58:59]
	s_mov_b32 m0, s14
	s_mov_b64 s[68:69], 0x60000
	v_readfirstlane_b32 s14, v139
	v_add_u32_e32 v140, 0x4000, v136
	global_load_lds_dwordx4 v[10:11], off
	v_lshl_add_u64 v[10:11], v[0:1], 0, s[68:69]
	s_mov_b32 m0, s14
	v_readfirstlane_b32 s14, v140
	v_add_u32_e32 v141, 0x6000, v136
	global_load_lds_dwordx4 v[10:11], off
	v_lshl_add_u64 v[10:11], v[2:3], 0, s[58:59]
	s_mov_b32 m0, s14
	v_readfirstlane_b32 s14, v141
	global_load_lds_dwordx4 v[10:11], off
	v_lshl_add_u64 v[10:11], v[2:3], 0, s[68:69]
	s_mov_b32 m0, s14
	v_ashrrev_i32_e32 v9, 8, v131
	global_load_lds_dwordx4 v[10:11], off
	v_cmp_eq_u32_e32 vcc, 1, v9
	v_readlane_b32 s70, v255, 41
	v_readlane_b32 s71, v255, 42
	v_readlane_b32 s74, v255, 45
	v_readlane_b32 s75, v255, 46
	s_and_saveexec_b64 s[14:15], vcc
	s_cbranch_execz .LBB0_208
	s_barrier

; DEV int opaque_tid512() { int t = threadIdx.x; asm volatile("" : "+v"(t)); return t; }
;   #define STAGE(P,BASE,LD,br,kt) do{ const HALF* _u=(BASE)+(long)(br)*(((&(LD))==&lda)?lda_u:(LD))+(long)(kt)*G_BK; \
;     for(int _i=0;_i<2;++_i){ \
;       __builtin_amdgcn_global_load_lds((const unsigned*)(_u+(long)_i*(((&(LD))==&lda)?stepa:stepb)+((&(LD))==&lda?oa0:ob0)), \
;         (unsigned*)((char*)(P)+t5*16+_i*8192),16,0,0);}}while(0)
;   #define BAR __builtin_amdgcn_s_barrier()
;     ...
;   const int t5=opaque_tid512();
;   const int wid=t5>>6,lane=t5&63,wr=wid>>2,wc=wid&3,fr=lane&15,fq=lane>>4;
;   h8 At[4][2],B0[2][2],B1[2][2];
;   const int nt=K/G_BK;
;   const int _ob=fr*64+fq*16, _sw=_ob^(((_ob>>9)&1)<<5);
;   const char* la=(const char*)shm+wr*8192+_sw;
;   const char* lb=(const char*)shm+65536+wc*4096+_sw;
;   unsigned oa0, ob0;
;   const int stepa = n2 ? 1024 : 64 * lda, stepb = 64 * ldb;
;   const int lda_u = n2 ? 16 : lda;
;   {int _b=t5*16;int _r,_c;g_stage_rc(_b,_r,_c);
;     oa0=n2 ? (unsigned)((n2*(_r&63)+(_r>>6))*1024+_c) : (unsigned)(_r*lda+_c); ob0=(unsigned)(_r*ldb+_c);}
;   STAGE(SB(0,0),Bt,ldb,0,0); STAGE(SA(0,0),A,lda,0,0);
;   STAGE(SB(0,1),Bt,ldb,G_HALF,0); STAGE(SA(0,1),A,lda,G_HALF,0);
;   if(wr==1)BAR;
; template <int ACT, bool TRANS>
; __device__ void job_gemm1_g(const P& p, int g, int ct2, int rt, HALF* dst, int ld, int cofs, HALF* sm) {
;     ...
;   const HALF* Ap = (const HALF*)(ws + OFF_X16) + (size_t)(g * GT_ + rt * 256) * 1024;
;   const HALF* Bp = (const HALF*)(ws + OFF_WIN) + (size_t)(ct2 * 256) * 1024;
;   f4 acc[2][2][4][2];
;   zero_acc256(acc);
;   asm volatile("s_waitcnt vmcnt(0)" ::: "memory");
;   __syncthreads();
;   if (TRANS) gemm256(acc, Ap, 1024, Bp, 1024, 1024, sm);
.LBB0_241:
	s_andn2_b64 vcc, exec, s[0:1]
	s_cbranch_vccnz .LBB0_257
	v_readlane_b32 s68, v255, 39
	v_readlane_b32 s72, v255, 43
	v_readlane_b32 s73, v255, 44
	v_mov_b32_e32 v130, v155
	s_mov_b64 s[6:7], s[72:73]
	v_mov_b32_e32 v131, v155
	s_lshl_b32 s21, s9, 8
	v_ashrrev_i32_e32 v0, 31, v131
	v_lshrrev_b32_e32 v0, 26, v0
	v_add_u32_e32 v0, v131, v0
	v_ashrrev_i32_e32 v4, 6, v0
	v_bfe_i32 v0, v131, 27, 1
	v_lshlrev_b32_e32 v5, 4, v131
	v_lshrrev_b32_e32 v0, 22, v0
	v_add_u32_e32 v0, v5, v0
	v_and_b32_e32 v0, 0xfffffc00, v0
	v_sub_u32_e32 v0, v5, v0
	v_lshrrev_b32_e32 v1, 4, v0
	v_bitop3_b32 v1, v1, v0, 32 bitop3:0x6c
	v_ashrrev_i32_e32 v0, 31, v0
	s_or_b32 s44, s21, s20
	v_lshrrev_b32_e32 v0, 26, v0
	s_lshl_b64 s[0:1], s[44:45], 11
	v_lshlrev_b32_e32 v2, 3, v4
	v_add_u32_e32 v0, v1, v0
	s_add_u32 s0, s6, s0
	v_and_b32_e32 v2, 0x3ffff0, v2
	v_ashrrev_i32_e32 v6, 6, v0
	s_addc_u32 s1, s7, s1
	v_add_u32_e32 v0, v6, v2
	v_lshlrev_b32_e32 v2, 5, v4
	s_add_u32 s0, s0, 0x3eb0000
	v_and_b32_e32 v7, 32, v2
	v_mul_i32_i24_e32 v2, 64, v6
	s_addc_u32 s1, s1, 0
	s_lshl_b32 s44, s8, 18
	v_sub_u32_e32 v1, v1, v2
	s_lshl_b64 s[2:3], s[44:45], 1
	v_ashrrev_i16_sdwa v8, v174, sext(v1) dst_sel:DWORD dst_unused:UNUSED_PAD src0_sel:DWORD src1_sel:BYTE_0
	v_lshl_or_b32 v0, v0, 10, v7
	s_add_u32 s12, s6, s2
	v_add_u32_sdwa v152, v0, sext(v8) dst_sel:DWORD dst_unused:UNUSED_PAD src0_sel:DWORD src1_sel:WORD_0
	v_add_u32_e32 v134, s95, v5
	s_addc_u32 s13, s7, s3
	v_lshlrev_b64 v[2:3], 1, v[152:153]
	v_readfirstlane_b32 s14, v134
	v_add_u32_e32 v135, 0x2000, v134
	v_lshl_add_u64 v[0:1], s[12:13], 0, v[2:3]
	s_mov_b32 m0, s14
	s_mov_b64 s[58:59], 0x20000
	v_readfirstlane_b32 s14, v135
	v_add_u32_e32 v136, 0, v5
	s_waitcnt vmcnt(0)
	s_waitcnt lgkmcnt(0)
	s_barrier
	global_load_lds_dwordx4 v[0:1], off
	v_lshl_add_u64 v[10:11], v[0:1], 0, s[58:59]
	s_mov_b32 m0, s14
	v_readfirstlane_b32 s14, v136
	v_add_u32_e32 v137, 0x2000, v136
	global_load_lds_dwordx4 v[10:11], off
	v_lshl_add_u64 v[2:3], s[0:1], 0, v[2:3]
	s_mov_b32 m0, s14
	v_readfirstlane_b32 s14, v137
	v_add_u32_e32 v138, s28, v5
	v_readlane_b32 s69, v255, 40
	global_load_lds_dwordx4 v[2:3], off
	v_lshl_add_u64 v[10:11], v[2:3], 0, s[58:59]
	s_mov_b32 m0, s14
	s_mov_b64 s[58:59], 0x40000
	v_readfirstlane_b32 s14, v138
	v_add_u32_e32 v139, 0x2000, v138
	global_load_lds_dwordx4 v[10:11], off
	v_lshl_add_u64 v[10:11], v[0:1], 0, s[58:59]
	s_mov_b32 m0, s14
	s_mov_b64 s[68:69], 0x60000
	v_readfirstlane_b32 s14, v139
	v_add_u32_e32 v140, 0x4000, v136
	global_load_lds_dwordx4 v[10:11], off
	v_lshl_add_u64 v[10:11], v[0:1], 0, s[68:69]
	s_mov_b32 m0, s14
	v_readfirstlane_b32 s14, v140
	v_add_u32_e32 v141, 0x6000, v136
	global_load_lds_dwordx4 v[10:11], off
	v_lshl_add_u64 v[10:11], v[2:3], 0, s[58:59]
	s_mov_b32 m0, s14
	v_readfirstlane_b32 s14, v141
	global_load_lds_dwordx4 v[10:11], off
	v_lshl_add_u64 v[10:11], v[2:3], 0, s[68:69]
	s_mov_b32 m0, s14
	v_ashrrev_i32_e32 v9, 8, v131
	global_load_lds_dwordx4 v[10:11], off
	v_cmp_eq_u32_e32 vcc, 1, v9
	v_readlane_b32 s70, v255, 41
	v_readlane_b32 s71, v255, 42
	v_readlane_b32 s74, v255, 45
	v_readlane_b32 s75, v255, 46
	s_and_saveexec_b64 s[14:15], vcc
	s_cbranch_execz .LBB0_244
	s_barrier

; DEV int opaque_tid512() { int t = threadIdx.x; asm volatile("" : "+v"(t)); return t; }
;   #define STAGE(P,BASE,LD,br,kt) do{ const HALF* _u=(BASE)+(long)(br)*(((&(LD))==&lda)?lda_u:(LD))+(long)(kt)*G_BK; \
;     for(int _i=0;_i<2;++_i){ \
;       __builtin_amdgcn_global_load_lds((const unsigned*)(_u+(long)_i*(((&(LD))==&lda)?stepa:stepb)+((&(LD))==&lda?oa0:ob0)), \
;         (unsigned*)((char*)(P)+t5*16+_i*8192),16,0,0);}}while(0)
;   #define BAR __builtin_amdgcn_s_barrier()
;     ...
;   const int t5=opaque_tid512();
;   const int wid=t5>>6,lane=t5&63,wr=wid>>2,wc=wid&3,fr=lane&15,fq=lane>>4;
;   h8 At[4][2],B0[2][2],B1[2][2];
;   const int nt=K/G_BK;
;   const int _ob=fr*64+fq*16, _sw=_ob^(((_ob>>9)&1)<<5);
;   const char* la=(const char*)shm+wr*8192+_sw;
;   const char* lb=(const char*)shm+65536+wc*4096+_sw;
;   unsigned oa0, ob0;
;   const int stepa = n2 ? 1024 : 64 * lda, stepb = 64 * ldb;
;   const int lda_u = n2 ? 16 : lda;
;   {int _b=t5*16;int _r,_c;g_stage_rc(_b,_r,_c);
;     oa0=n2 ? (unsigned)((n2*(_r&63)+(_r>>6))*1024+_c) : (unsigned)(_r*lda+_c); ob0=(unsigned)(_r*ldb+_c);}
;   STAGE(SB(0,0),Bt,ldb,0,0); STAGE(SA(0,0),A,lda,0,0);
;   STAGE(SB(0,1),Bt,ldb,G_HALF,0); STAGE(SA(0,1),A,lda,G_HALF,0);
;   if(wr==1)BAR;
; template <int ACT, bool TRANS>
; __device__ void job_gemm1_g(const P& p, int g, int ct2, int rt, HALF* dst, int ld, int cofs, HALF* sm) {
;     ...
;   const HALF* Ap = (const HALF*)(ws + OFF_X16) + (size_t)(g * GT_ + rt * 256) * 1024;
;   const HALF* Bp = (const HALF*)(ws + OFF_WIN) + (size_t)(ct2 * 256) * 1024;
;   f4 acc[2][2][4][2];
;   zero_acc256(acc);
;   asm volatile("s_waitcnt vmcnt(0)" ::: "memory");
;   __syncthreads();
;   if (TRANS) gemm256(acc, Ap, 1024, Bp, 1024, 1024, sm);
;   else gemm256(acc, Bp, 1024, Ap, 1024, 1024, sm);
.LBB0_258:
	s_andn2_b64 vcc, exec, s[0:1]
	s_cbranch_vccnz .LBB0_274
	v_readlane_b32 s68, v255, 39
	v_readlane_b32 s72, v255, 43
	v_readlane_b32 s73, v255, 44
	v_mov_b32_e32 v130, v155
	s_mov_b64 s[2:3], s[72:73]
	v_mov_b32_e32 v131, v155
	s_lshl_b32 s14, s9, 8
	v_ashrrev_i32_e32 v0, 31, v131
	v_lshrrev_b32_e32 v0, 26, v0
	v_add_u32_e32 v0, v131, v0
	v_ashrrev_i32_e32 v4, 6, v0
	v_bfe_i32 v0, v131, 27, 1
	v_lshlrev_b32_e32 v5, 4, v131
	v_lshrrev_b32_e32 v0, 22, v0
	v_add_u32_e32 v0, v5, v0
	v_and_b32_e32 v0, 0xfffffc00, v0
	v_sub_u32_e32 v0, v5, v0
	v_lshrrev_b32_e32 v1, 4, v0
	v_bitop3_b32 v1, v1, v0, 32 bitop3:0x6c
	v_ashrrev_i32_e32 v0, 31, v0
	v_lshrrev_b32_e32 v0, 26, v0
	v_lshlrev_b32_e32 v2, 3, v4
	v_add_u32_e32 v0, v1, v0
	s_or_b32 s44, s14, s20
	v_and_b32_e32 v2, 0x3ffff0, v2
	v_ashrrev_i32_e32 v6, 6, v0
	s_lshl_b64 s[0:1], s[44:45], 11
	v_add_u32_e32 v0, v6, v2
	v_lshlrev_b32_e32 v2, 5, v4
	s_add_u32 s0, s2, s0
	v_and_b32_e32 v7, 32, v2
	v_mul_i32_i24_e32 v2, 64, v6
	s_addc_u32 s1, s3, s1
	v_sub_u32_e32 v1, v1, v2
	s_add_u32 s6, s0, 0x3eb0000
	v_ashrrev_i16_sdwa v8, v174, sext(v1) dst_sel:DWORD dst_unused:UNUSED_PAD src0_sel:DWORD src1_sel:BYTE_0
	v_lshl_or_b32 v0, v0, 10, v7
	s_addc_u32 s7, s1, 0
	s_lshl_b32 s44, s8, 18
	v_add_u32_sdwa v152, v0, sext(v8) dst_sel:DWORD dst_unused:UNUSED_PAD src0_sel:DWORD src1_sel:WORD_0
	v_add_u32_e32 v134, s95, v5
	s_lshl_b64 s[0:1], s[44:45], 1
	v_lshlrev_b64 v[2:3], 1, v[152:153]
	v_readfirstlane_b32 s12, v134
	v_add_u32_e32 v135, 0x2000, v134
	s_add_u32 s0, s2, s0
	v_lshl_add_u64 v[0:1], s[6:7], 0, v[2:3]
	s_mov_b32 m0, s12
	s_mov_b64 s[58:59], 0x20000
	v_readfirstlane_b32 s12, v135
	v_add_u32_e32 v136, 0, v5
	s_addc_u32 s1, s3, s1
	s_waitcnt vmcnt(0)
	s_waitcnt lgkmcnt(0)
	s_barrier
	global_load_lds_dwordx4 v[0:1], off
	v_lshl_add_u64 v[10:11], v[0:1], 0, s[58:59]
	s_mov_b32 m0, s12
	v_readfirstlane_b32 s12, v136
	v_add_u32_e32 v137, 0x2000, v136
	global_load_lds_dwordx4 v[10:11], off
	v_lshl_add_u64 v[2:3], s[0:1], 0, v[2:3]
	s_mov_b32 m0, s12
	v_readfirstlane_b32 s12, v137
	v_add_u32_e32 v138, s28, v5
	v_readlane_b32 s69, v255, 40
	global_load_lds_dwordx4 v[2:3], off
	v_lshl_add_u64 v[10:11], v[2:3], 0, s[58:59]
	s_mov_b32 m0, s12
	s_mov_b64 s[58:59], 0x40000
	v_readfirstlane_b32 s12, v138
	v_add_u32_e32 v139, 0x2000, v138
	global_load_lds_dwordx4 v[10:11], off
	v_lshl_add_u64 v[10:11], v[0:1], 0, s[58:59]
	s_mov_b32 m0, s12
	s_mov_b64 s[68:69], 0x60000
	v_readfirstlane_b32 s12, v139
	v_add_u32_e32 v140, 0x4000, v136
	global_load_lds_dwordx4 v[10:11], off
	v_lshl_add_u64 v[10:11], v[0:1], 0, s[68:69]
	s_mov_b32 m0, s12
	v_readfirstlane_b32 s12, v140
	v_add_u32_e32 v141, 0x6000, v136
	global_load_lds_dwordx4 v[10:11], off
	v_lshl_add_u64 v[10:11], v[2:3], 0, s[58:59]
	s_mov_b32 m0, s12
	v_readfirstlane_b32 s12, v141
	global_load_lds_dwordx4 v[10:11], off
	v_lshl_add_u64 v[10:11], v[2:3], 0, s[68:69]
	s_mov_b32 m0, s12
	v_ashrrev_i32_e32 v9, 8, v131
	global_load_lds_dwordx4 v[10:11], off
	v_cmp_eq_u32_e32 vcc, 1, v9
	v_readlane_b32 s70, v255, 41
	v_readlane_b32 s71, v255, 42
	v_readlane_b32 s74, v255, 45
	v_readlane_b32 s75, v255, 46
	s_and_saveexec_b64 s[12:13], vcc
	s_cbranch_execz .LBB0_261
	s_barrier

; DEV int opaque_tid512() { int t = threadIdx.x; asm volatile("" : "+v"(t)); return t; }
;   #define STAGE(P,BASE,LD,br,kt) do{ const HALF* _u=(BASE)+(long)(br)*(((&(LD))==&lda)?lda_u:(LD))+(long)(kt)*G_BK; \
;     for(int _i=0;_i<2;++_i){ \
;       __builtin_amdgcn_global_load_lds((const unsigned*)(_u+(long)_i*(((&(LD))==&lda)?stepa:stepb)+((&(LD))==&lda?oa0:ob0)), \
;         (unsigned*)((char*)(P)+t5*16+_i*8192),16,0,0);}}while(0)
;   #define BAR __builtin_amdgcn_s_barrier()
;     ...
;   const int t5=opaque_tid512();
;   const int wid=t5>>6,lane=t5&63,wr=wid>>2,wc=wid&3,fr=lane&15,fq=lane>>4;
;   h8 At[4][2],B0[2][2],B1[2][2];
;   const int nt=K/G_BK;
;   const int _ob=fr*64+fq*16, _sw=_ob^(((_ob>>9)&1)<<5);
;   const char* la=(const char*)shm+wr*8192+_sw;
;   const char* lb=(const char*)shm+65536+wc*4096+_sw;
;   unsigned oa0, ob0;
;   const int stepa = n2 ? 1024 : 64 * lda, stepb = 64 * ldb;
;   const int lda_u = n2 ? 16 : lda;
;   {int _b=t5*16;int _r,_c;g_stage_rc(_b,_r,_c);
;     oa0=n2 ? (unsigned)((n2*(_r&63)+(_r>>6))*1024+_c) : (unsigned)(_r*lda+_c); ob0=(unsigned)(_r*ldb+_c);}
;   STAGE(SB(0,0),Bt,ldb,0,0); STAGE(SA(0,0),A,lda,0,0);
;   STAGE(SB(0,1),Bt,ldb,G_HALF,0); STAGE(SA(0,1),A,lda,G_HALF,0);
;   if(wr==1)BAR;
; template <int ACT, bool TRANS>
; __device__ void job_gemm1_g(const P& p, int g, int ct2, int rt, HALF* dst, int ld, int cofs, HALF* sm) {
;     ...
;   const HALF* Ap = (const HALF*)(ws + OFF_X16) + (size_t)(g * GT_ + rt * 256) * 1024;
;   const HALF* Bp = (const HALF*)(ws + OFF_WIN) + (size_t)(ct2 * 256) * 1024;
;   f4 acc[2][2][4][2];
;   zero_acc256(acc);
;   asm volatile("s_waitcnt vmcnt(0)" ::: "memory");
;   __syncthreads();
;   if (TRANS) gemm256(acc, Ap, 1024, Bp, 1024, 1024, sm);
;   else gemm256(acc, Bp, 1024, Ap, 1024, 1024, sm);
.LBB0_292:
	v_readlane_b32 s68, v255, 39
	v_readlane_b32 s72, v255, 43
	v_readlane_b32 s73, v255, 44
	v_mov_b32_e32 v130, v155
	s_mov_b64 s[2:3], s[72:73]
	v_mov_b32_e32 v131, v155
	s_lshl_b32 s9, s9, 8
	v_ashrrev_i32_e32 v0, 31, v131
	v_lshrrev_b32_e32 v0, 26, v0
	v_add_u32_e32 v0, v131, v0
	v_ashrrev_i32_e32 v4, 6, v0
	v_bfe_i32 v0, v131, 27, 1
	v_lshlrev_b32_e32 v5, 4, v131
	v_lshrrev_b32_e32 v0, 22, v0
	v_add_u32_e32 v0, v5, v0
	v_and_b32_e32 v0, 0xfffffc00, v0
	v_sub_u32_e32 v0, v5, v0
	v_lshrrev_b32_e32 v1, 4, v0
	v_bitop3_b32 v1, v1, v0, 32 bitop3:0x6c
	v_ashrrev_i32_e32 v0, 31, v0
	v_lshrrev_b32_e32 v0, 26, v0
	v_lshlrev_b32_e32 v2, 3, v4
	v_add_u32_e32 v0, v1, v0
	s_or_b32 s44, s9, s20
	v_and_b32_e32 v2, 0x3ffff0, v2
	v_ashrrev_i32_e32 v6, 6, v0
	s_lshl_b64 s[0:1], s[44:45], 11
	v_add_u32_e32 v0, v6, v2
	v_lshlrev_b32_e32 v2, 5, v4
	s_add_u32 s0, s2, s0
	v_and_b32_e32 v7, 32, v2
	v_mul_i32_i24_e32 v2, 64, v6
	s_addc_u32 s1, s3, s1
	v_sub_u32_e32 v1, v1, v2
	s_add_u32 s6, s0, 0x3eb0000
	v_ashrrev_i16_sdwa v8, v174, sext(v1) dst_sel:DWORD dst_unused:UNUSED_PAD src0_sel:DWORD src1_sel:BYTE_0
	v_lshl_or_b32 v0, v0, 10, v7
	s_addc_u32 s7, s1, 0
	s_lshl_b32 s44, s8, 8
	v_add_u32_sdwa v152, v0, sext(v8) dst_sel:DWORD dst_unused:UNUSED_PAD src0_sel:DWORD src1_sel:WORD_0
	v_add_u32_e32 v134, s95, v5
	s_lshl_b64 s[0:1], s[44:45], 11
	v_lshlrev_b64 v[2:3], 1, v[152:153]
	v_readfirstlane_b32 s8, v134
	v_add_u32_e32 v135, 0x2000, v134
	s_add_u32 s0, s2, s0
	v_lshl_add_u64 v[0:1], s[6:7], 0, v[2:3]
	s_mov_b32 m0, s8
	s_mov_b64 s[12:13], 0x20000
	v_readfirstlane_b32 s8, v135
	v_add_u32_e32 v136, 0, v5
	s_addc_u32 s1, s3, s1
	s_waitcnt vmcnt(0)
	s_waitcnt lgkmcnt(0)
	s_barrier
	global_load_lds_dwordx4 v[0:1], off
	v_lshl_add_u64 v[10:11], v[0:1], 0, s[12:13]
	s_mov_b32 m0, s8
	v_readfirstlane_b32 s8, v136
	v_add_u32_e32 v137, 0x2000, v136
	global_load_lds_dwordx4 v[10:11], off
	v_lshl_add_u64 v[2:3], s[0:1], 0, v[2:3]
	s_mov_b32 m0, s8
	v_readfirstlane_b32 s8, v137
	v_add_u32_e32 v138, s28, v5
	global_load_lds_dwordx4 v[2:3], off
	v_lshl_add_u64 v[10:11], v[2:3], 0, s[12:13]
	s_mov_b32 m0, s8
	s_mov_b64 s[12:13], 0x40000
	v_readfirstlane_b32 s8, v138
	v_add_u32_e32 v139, 0x2000, v138
	global_load_lds_dwordx4 v[10:11], off
	v_lshl_add_u64 v[10:11], v[0:1], 0, s[12:13]
	s_mov_b32 m0, s8
	s_mov_b64 s[14:15], 0x60000
	v_readfirstlane_b32 s8, v139
	v_add_u32_e32 v140, 0x4000, v136
	global_load_lds_dwordx4 v[10:11], off
	v_lshl_add_u64 v[10:11], v[0:1], 0, s[14:15]
	s_mov_b32 m0, s8
	v_readfirstlane_b32 s8, v140
	v_add_u32_e32 v141, 0x6000, v136
	global_load_lds_dwordx4 v[10:11], off
	v_lshl_add_u64 v[10:11], v[2:3], 0, s[12:13]
	s_mov_b32 m0, s8
	v_readfirstlane_b32 s8, v141
	global_load_lds_dwordx4 v[10:11], off
	v_lshl_add_u64 v[10:11], v[2:3], 0, s[14:15]
	s_mov_b32 m0, s8
	v_ashrrev_i32_e32 v9, 8, v131
	global_load_lds_dwordx4 v[10:11], off
	v_cmp_eq_u32_e32 vcc, 1, v9
	v_readlane_b32 s69, v255, 40
	v_readlane_b32 s70, v255, 41
	v_readlane_b32 s71, v255, 42
	v_readlane_b32 s74, v255, 45
	v_readlane_b32 s75, v255, 46
	s_and_saveexec_b64 s[12:13], vcc
	s_cbranch_execz .LBB0_294
	s_barrier

; DEV int opaque_tid512() { int t = threadIdx.x; asm volatile("" : "+v"(t)); return t; }
;   #define STAGE(P,BASE,LD,br,kt) do{ const HALF* _u=(BASE)+(long)(br)*(((&(LD))==&lda)?lda_u:(LD))+(long)(kt)*G_BK; \
;     for(int _i=0;_i<2;++_i){ \
;       __builtin_amdgcn_global_load_lds((const unsigned*)(_u+(long)_i*(((&(LD))==&lda)?stepa:stepb)+((&(LD))==&lda?oa0:ob0)), \
;         (unsigned*)((char*)(P)+t5*16+_i*8192),16,0,0);}}while(0)
;   #define BAR __builtin_amdgcn_s_barrier()
;     ...
;   const int t5=opaque_tid512();
;   const int wid=t5>>6,lane=t5&63,wr=wid>>2,wc=wid&3,fr=lane&15,fq=lane>>4;
;   h8 At[4][2],B0[2][2],B1[2][2];
;   const int nt=K/G_BK;
;   const int _ob=fr*64+fq*16, _sw=_ob^(((_ob>>9)&1)<<5);
;   const char* la=(const char*)shm+wr*8192+_sw;
;   const char* lb=(const char*)shm+65536+wc*4096+_sw;
;   unsigned oa0, ob0;
;   const int stepa = n2 ? 1024 : 64 * lda, stepb = 64 * ldb;
;   const int lda_u = n2 ? 16 : lda;
;   {int _b=t5*16;int _r,_c;g_stage_rc(_b,_r,_c);
;     oa0=n2 ? (unsigned)((n2*(_r&63)+(_r>>6))*1024+_c) : (unsigned)(_r*lda+_c); ob0=(unsigned)(_r*ldb+_c);}
;   STAGE(SB(0,0),Bt,ldb,0,0); STAGE(SA(0,0),A,lda,0,0);
;   STAGE(SB(0,1),Bt,ldb,G_HALF,0); STAGE(SA(0,1),A,lda,G_HALF,0);
;   if(wr==1)BAR;
; template <int K>
; __device__ void job_resid_g(const P& p, const HALF* A, const HALF* Bt, int job, HALF* sm) {
;     ...
;   const int ct2 = job & 3, rt = job >> 2;
;   const HALF* Ap = A + (size_t)(rt * 256) * K;
;   const HALF* Bp = Bt + (size_t)(ct2 * 256) * K;
;   f4 acc[2][2][4][2];
;   zero_acc256(acc);
;   asm volatile("s_waitcnt vmcnt(0)" ::: "memory");
;   __syncthreads();
;   gemm256(acc, Ap, K, Bp, K, K, sm);
.LBB0_320:
	v_readlane_b32 s68, v255, 39
	v_readlane_b32 s72, v255, 43
	v_readlane_b32 s73, v255, 44
	v_mov_b32_e32 v130, v155
	s_mov_b64 s[2:3], s[72:73]
	v_mov_b32_e32 v131, v155
	s_mul_i32 s0, s21, s8
	v_ashrrev_i32_e32 v0, 31, v131
	v_lshrrev_b32_e32 v0, 26, v0
	v_add_u32_e32 v0, v131, v0
	v_ashrrev_i32_e32 v4, 6, v0
	v_bfe_i32 v0, v131, 27, 1
	v_lshlrev_b32_e32 v5, 4, v131
	v_lshrrev_b32_e32 v0, 22, v0
	v_add_u32_e32 v0, v5, v0
	v_and_b32_e32 v0, 0xfffffc00, v0
	v_sub_u32_e32 v0, v5, v0
	s_add_i32 s12, s0, s9
	v_lshrrev_b32_e32 v1, 4, v0
	v_bitop3_b32 v1, v1, v0, 32 bitop3:0x6c
	v_ashrrev_i32_e32 v0, 31, v0
	s_lshl_b32 s1, s12, 6
	s_and_b32 s1, s1, 0xfffff800
	s_lshl_b32 s0, s12, 8
	s_and_b32 s0, s0, 0x700
	s_or_b32 s0, s0, s1
	v_lshrrev_b32_e32 v0, 26, v0
	s_ashr_i32 s1, s0, 31
	v_lshlrev_b32_e32 v2, 3, v4
	v_add_u32_e32 v0, v1, v0
	s_lshl_b64 s[6:7], s[0:1], 11
	v_readlane_b32 s1, v254, 53
	v_and_b32_e32 v2, 0x3ffff0, v2
	v_ashrrev_i32_e32 v6, 6, v0
	s_add_u32 s10, s1, s6
	v_readlane_b32 s1, v254, 54
	v_add_u32_e32 v0, v6, v2
	v_lshlrev_b32_e32 v2, 5, v4
	s_addc_u32 s11, s1, s7
	s_lshl_b32 s1, s12, 5
	v_and_b32_e32 v7, 32, v2
	v_mul_i32_i24_e32 v2, 64, v6
	s_and_b32 s1, s1, 0x300
	v_sub_u32_e32 v1, v1, v2
	s_lshl_b32 s12, s1, 11
	v_readlane_b32 s13, v254, 55
	v_ashrrev_i16_sdwa v8, v174, sext(v1) dst_sel:DWORD dst_unused:UNUSED_PAD src0_sel:DWORD src1_sel:BYTE_0
	v_lshl_or_b32 v0, v0, 10, v7
	s_add_u32 s12, s13, s12
	v_readlane_b32 s13, v254, 56
	v_add_u32_sdwa v152, v0, sext(v8) dst_sel:DWORD dst_unused:UNUSED_PAD src0_sel:DWORD src1_sel:WORD_0
	v_add_u32_e32 v134, s95, v5
	s_addc_u32 s13, s13, 0
	v_lshlrev_b64 v[2:3], 1, v[152:153]
	v_readfirstlane_b32 s14, v134
	v_add_u32_e32 v135, 0x2000, v134
	v_lshl_add_u64 v[0:1], s[12:13], 0, v[2:3]
	s_mov_b32 m0, s14
	s_mov_b64 s[22:23], 0x20000
	v_readfirstlane_b32 s14, v135
	v_add_u32_e32 v136, 0, v5
	s_waitcnt vmcnt(0)
	s_waitcnt lgkmcnt(0)
	s_barrier
	global_load_lds_dwordx4 v[0:1], off
	v_lshl_add_u64 v[10:11], v[0:1], 0, s[22:23]
	s_mov_b32 m0, s14
	v_readfirstlane_b32 s14, v136
	v_add_u32_e32 v137, 0x2000, v136
	global_load_lds_dwordx4 v[10:11], off
	v_lshl_add_u64 v[2:3], s[10:11], 0, v[2:3]
	s_mov_b32 m0, s14
	v_readfirstlane_b32 s14, v137
	v_add_u32_e32 v138, s28, v5
	global_load_lds_dwordx4 v[2:3], off
	v_lshl_add_u64 v[10:11], v[2:3], 0, s[22:23]
	s_mov_b32 m0, s14
	s_mov_b64 s[22:23], 0x40000
	v_readfirstlane_b32 s14, v138
	v_add_u32_e32 v139, 0x2000, v138
	global_load_lds_dwordx4 v[10:11], off
	v_lshl_add_u64 v[10:11], v[0:1], 0, s[22:23]
	s_mov_b32 m0, s14
	s_mov_b64 s[58:59], 0x60000
	v_readfirstlane_b32 s14, v139
	v_add_u32_e32 v140, 0x4000, v136
	global_load_lds_dwordx4 v[10:11], off
	v_lshl_add_u64 v[10:11], v[0:1], 0, s[58:59]
	s_mov_b32 m0, s14
	v_readfirstlane_b32 s14, v140
	v_add_u32_e32 v141, 0x6000, v136
	global_load_lds_dwordx4 v[10:11], off
	v_lshl_add_u64 v[10:11], v[2:3], 0, s[22:23]
	s_mov_b32 m0, s14
	v_readfirstlane_b32 s14, v141
	global_load_lds_dwordx4 v[10:11], off
	v_lshl_add_u64 v[10:11], v[2:3], 0, s[58:59]
	s_mov_b32 m0, s14
	v_ashrrev_i32_e32 v9, 8, v131
	global_load_lds_dwordx4 v[10:11], off
	v_cmp_eq_u32_e32 vcc, 1, v9
	v_readlane_b32 s69, v255, 40
	v_readlane_b32 s70, v255, 41
	v_readlane_b32 s71, v255, 42
	v_readlane_b32 s74, v255, 45
	v_readlane_b32 s75, v255, 46
	s_and_saveexec_b64 s[14:15], vcc
	s_cbranch_execz .LBB0_322
	s_barrier

; DEV int opaque_tid512() { int t = threadIdx.x; asm volatile("" : "+v"(t)); return t; }
;   #define STAGE(P,BASE,LD,br,kt) do{ const HALF* _u=(BASE)+(long)(br)*(((&(LD))==&lda)?lda_u:(LD))+(long)(kt)*G_BK; \
;     for(int _i=0;_i<2;++_i){ \
;       __builtin_amdgcn_global_load_lds((const unsigned*)(_u+(long)_i*(((&(LD))==&lda)?stepa:stepb)+((&(LD))==&lda?oa0:ob0)), \
;         (unsigned*)((char*)(P)+t5*16+_i*8192),16,0,0);}}while(0)
;   #define BAR __builtin_amdgcn_s_barrier()
;     ...
;   const int t5=opaque_tid512();
;   const int wid=t5>>6,lane=t5&63,wr=wid>>2,wc=wid&3,fr=lane&15,fq=lane>>4;
;   h8 At[4][2],B0[2][2],B1[2][2];
;   const int nt=K/G_BK;
;   const int _ob=fr*64+fq*16, _sw=_ob^(((_ob>>9)&1)<<5);
;   const char* la=(const char*)shm+wr*8192+_sw;
;   const char* lb=(const char*)shm+65536+wc*4096+_sw;
;   unsigned oa0, ob0;
;   const int stepa = n2 ? 1024 : 64 * lda, stepb = 64 * ldb;
;   const int lda_u = n2 ? 16 : lda;
;   {int _b=t5*16;int _r,_c;g_stage_rc(_b,_r,_c);
;     oa0=n2 ? (unsigned)((n2*(_r&63)+(_r>>6))*1024+_c) : (unsigned)(_r*lda+_c); ob0=(unsigned)(_r*ldb+_c);}
;   STAGE(SB(0,0),Bt,ldb,0,0); STAGE(SA(0,0),A,lda,0,0);
;   STAGE(SB(0,1),Bt,ldb,G_HALF,0); STAGE(SA(0,1),A,lda,G_HALF,0);
;   if(wr==1)BAR;
; __device__ void job_scores_g(const P& p, int l, int job, HALF* sm) {
;     ...
;   const int h = job & 3, cgi = job >> 2;
;   const HALF* Kp = (const HALF*)(ws + G_K) + (size_t)(cgi * 256) * 1024 + h * 256;
;   const HALF* Qp = (const HALF*)(ws + G_Q) + (size_t)(cgi * 256) * 1024 + h * 256;
;   f4 acc[2][2][4][2];
;   zero_acc256(acc);
;   __syncthreads();
;   gemm256(acc, Kp, 1024, Qp, 1024, 256, sm);
.LBB0_377:
	s_cmpk_gt_i32 s10, 0x1ff
	s_mov_b64 s[0:1], -1
	s_cbranch_scc0 .LBB0_391
	v_readlane_b32 s12, v255, 39
	v_readlane_b32 s16, v255, 43
	v_readlane_b32 s17, v255, 44
	v_mov_b32_e32 v130, v155
	s_mov_b64 s[8:9], s[16:17]
	v_mov_b32_e32 v128, v155
	s_add_i32 s0, s10, 0xfffffe00
	v_bfe_i32 v1, v128, 27, 1
	v_lshlrev_b32_e32 v16, 4, v128
	v_lshrrev_b32_e32 v1, 22, v1
	v_add_u32_e32 v1, v16, v1
	v_and_b32_e32 v1, 0xfffffc00, v1
	v_ashrrev_i32_e32 v0, 31, v128
	v_sub_u32_e32 v1, v16, v1
	s_and_b32 s6, s10, 3
	s_lshr_b32 s2, s0, 2
	v_lshrrev_b32_e32 v0, 26, v0
	v_lshrrev_b32_e32 v2, 4, v1
	s_lshl_b32 s0, s2, 19
	s_lshl_b32 s3, s6, 9
	v_add_u32_e32 v0, v128, v0
	v_bitop3_b32 v2, v2, v1, 32 bitop3:0x6c
	v_ashrrev_i32_e32 v1, 31, v1
	s_add_u32 s0, s8, s0
	v_ashrrev_i32_e32 v0, 6, v0
	v_lshrrev_b32_e32 v1, 26, v1
	s_addc_u32 s1, s9, 0
	v_lshlrev_b32_e32 v3, 3, v0
	v_add_u32_e32 v1, v2, v1
	s_add_u32 s7, s0, s3
	v_and_b32_e32 v3, 0x3ffff0, v3
	v_ashrrev_i32_e32 v1, 6, v1
	s_addc_u32 s11, s1, 0
	v_add_u32_e32 v3, v1, v3
	v_lshlrev_b32_e32 v0, 5, v0
	v_mul_i32_i24_e32 v1, 64, v1
	s_add_u32 s0, s7, 0x1aeb0000
	v_and_b32_e32 v0, 32, v0
	v_sub_u32_e32 v1, v2, v1
	s_addc_u32 s1, s11, 0
	v_ashrrev_i16_sdwa v1, v174, sext(v1) dst_sel:DWORD dst_unused:UNUSED_PAD src0_sel:DWORD src1_sel:BYTE_0
	v_lshl_or_b32 v0, v3, 10, v0
	v_readlane_b32 s13, v255, 40
	s_add_u32 s12, s7, 0x19eb0000
	v_add_u32_sdwa v152, v0, sext(v1) dst_sel:DWORD dst_unused:UNUSED_PAD src0_sel:DWORD src1_sel:WORD_0
	v_add_u32_e32 v14, s95, v16
	s_addc_u32 s13, s11, 0
	v_lshlrev_b64 v[0:1], 1, v[152:153]
	v_readfirstlane_b32 s7, v14
	v_add_u32_e32 v15, 0x2000, v14
	v_lshl_add_u64 v[4:5], s[12:13], 0, v[0:1]
	s_mov_b32 m0, s7
	s_mov_b64 s[12:13], 0x20000
	v_readfirstlane_b32 s7, v15
	v_add_u32_e32 v12, 0, v16
	s_barrier
	global_load_lds_dwordx4 v[4:5], off
	v_lshl_add_u64 v[2:3], v[4:5], 0, s[12:13]
	s_mov_b32 m0, s7
	v_lshl_add_u64 v[0:1], s[0:1], 0, v[0:1]
	v_readfirstlane_b32 s0, v12
	v_add_u32_e32 v13, 0x2000, v12
	global_load_lds_dwordx4 v[2:3], off
	s_mov_b32 m0, s0
	v_readfirstlane_b32 s0, v13
	v_add_u32_e32 v10, s28, v16
	v_readlane_b32 s14, v255, 41
	v_readlane_b32 s15, v255, 42
	global_load_lds_dwordx4 v[0:1], off
	v_lshl_add_u64 v[2:3], v[0:1], 0, s[12:13]
	s_mov_b32 m0, s0
	s_mov_b64 s[12:13], 0x40000
	v_readfirstlane_b32 s0, v10
	v_add_u32_e32 v11, 0x2000, v10
	global_load_lds_dwordx4 v[2:3], off
	v_lshl_add_u64 v[2:3], v[4:5], 0, s[12:13]
	s_mov_b32 m0, s0
	s_mov_b64 s[14:15], 0x60000
	v_readfirstlane_b32 s0, v11
	v_add_u32_e32 v8, 0x4000, v12
	global_load_lds_dwordx4 v[2:3], off
	v_lshl_add_u64 v[6:7], v[4:5], 0, s[14:15]
	s_mov_b32 m0, s0
	v_readfirstlane_b32 s0, v8
	v_add_u32_e32 v9, 0x6000, v12
	global_load_lds_dwordx4 v[6:7], off
	v_lshl_add_u64 v[6:7], v[0:1], 0, s[12:13]
	s_mov_b32 m0, s0
	v_readfirstlane_b32 s0, v9
	global_load_lds_dwordx4 v[6:7], off
	v_lshl_add_u64 v[18:19], v[0:1], 0, s[14:15]
	s_mov_b32 m0, s0
	v_ashrrev_i32_e32 v17, 8, v128
	global_load_lds_dwordx4 v[18:19], off
	v_cmp_eq_u32_e32 vcc, 1, v17
	v_readlane_b32 s18, v255, 45
	v_readlane_b32 s19, v255, 46
	s_and_saveexec_b64 s[0:1], vcc
	s_cbranch_execz .LBB0_380
	s_barrier

; DEV int opaque_tid512() { int t = threadIdx.x; asm volatile("" : "+v"(t)); return t; }
;   #define STAGE(P,BASE,LD,br,kt) do{ const HALF* _u=(BASE)+(long)(br)*(((&(LD))==&lda)?lda_u:(LD))+(long)(kt)*G_BK; \
;     for(int _i=0;_i<2;++_i){ \
;       __builtin_amdgcn_global_load_lds((const unsigned*)(_u+(long)_i*(((&(LD))==&lda)?stepa:stepb)+((&(LD))==&lda?oa0:ob0)), \
;         (unsigned*)((char*)(P)+t5*16+_i*8192),16,0,0);}}while(0)
;   #define BAR __builtin_amdgcn_s_barrier()
;     ...
;   const int t5=opaque_tid512();
;   const int wid=t5>>6,lane=t5&63,wr=wid>>2,wc=wid&3,fr=lane&15,fq=lane>>4;
;   h8 At[4][2],B0[2][2],B1[2][2];
;   const int nt=K/G_BK;
;   const int _ob=fr*64+fq*16, _sw=_ob^(((_ob>>9)&1)<<5);
;   const char* la=(const char*)shm+wr*8192+_sw;
;   const char* lb=(const char*)shm+65536+wc*4096+_sw;
;   unsigned oa0, ob0;
;   const int stepa = n2 ? 1024 : 64 * lda, stepb = 64 * ldb;
;   const int lda_u = n2 ? 16 : lda;
;   {int _b=t5*16;int _r,_c;g_stage_rc(_b,_r,_c);
;     oa0=n2 ? (unsigned)((n2*(_r&63)+(_r>>6))*1024+_c) : (unsigned)(_r*lda+_c); ob0=(unsigned)(_r*ldb+_c);}
;   STAGE(SB(0,0),Bt,ldb,0,0); STAGE(SA(0,0),A,lda,0,0);
;   STAGE(SB(0,1),Bt,ldb,G_HALF,0); STAGE(SA(0,1),A,lda,G_HALF,0);
;   if(wr==1)BAR;
; __device__ void job_U_g(const P& p, int job, HALF* sm) {
;     ...
;   const int b2 = job & 1, dir = (job >> 1) & 1, h = (job >> 2) & 3, cgi = job >> 4;
;   const HALF* KT = (const HALF*)(ws + (dir ? G_KTB : G_KTF)) + (size_t)(h * 256) * 8192 + cgi * 256;
;   const HALF* VT = (const HALF*)(ws + G_VT) + (size_t)(h * 512 + b2 * 256) * 8192 + cgi * 256;
;   f4 acc[2][2][4][2];
;   zero_acc256(acc);
;   __syncthreads();
;   gemm256(acc, KT, 8192, VT, 8192, 256, sm);
.LBB0_391:
	s_and_b64 vcc, exec, s[0:1]
	s_cbranch_vccz .LBB0_376
	v_readlane_b32 s12, v255, 39
	s_bfe_u32 s7, s10, 0x10004
	s_bfe_u32 s6, s10, 0x20005
	s_and_b32 s8, s10, 7
	s_bfe_u32 s9, s10, 0x20007
	s_lshl_b32 s9, s9, 3
	s_or_b32 s8, s8, s9
	v_readlane_b32 s16, v255, 43
	v_readlane_b32 s17, v255, 44
	s_cmp_eq_u32 s7, 0
	s_mov_b32 s2, 0x1beb0000
	v_mov_b32_e32 v128, v155
	s_mov_b64 s[0:1], s[16:17]
	s_cselect_b32 s2, s2, 0x1ceb0000
	s_add_u32 s2, s0, s2
	s_addc_u32 s3, s1, 0
	s_lshl_b32 s9, s6, 22
	v_mov_b32_e32 v129, v155
	s_add_u32 s9, s2, s9
	s_addc_u32 s11, s3, 0
	v_bfe_i32 v1, v129, 27, 1
	s_lshl_b32 s2, s8, 8
	v_lshlrev_b32_e32 v16, 4, v129
	v_lshrrev_b32_e32 v1, 22, v1
	s_ashr_i32 s3, s2, 31
	v_add_u32_e32 v1, v16, v1
	s_lshl_b64 s[2:3], s[2:3], 1
	v_and_b32_e32 v1, 0xfffffc00, v1
	v_readlane_b32 s13, v255, 40
	s_add_u32 s12, s9, s2
	v_ashrrev_i32_e32 v0, 31, v129
	v_sub_u32_e32 v1, v16, v1
	s_addc_u32 s13, s11, s3
	s_lshl_b32 s9, s10, 5
	v_lshrrev_b32_e32 v0, 26, v0
	v_lshrrev_b32_e32 v2, 4, v1
	v_readlane_b32 s14, v255, 41
	s_and_b32 s9, s9, 0x100
	v_add_u32_e32 v0, v129, v0
	v_bitop3_b32 v2, v2, v1, 32 bitop3:0x6c
	v_ashrrev_i32_e32 v1, 31, v1
	s_lshl_b32 s11, s6, 23
	s_lshl_b32 s14, s9, 14
	v_ashrrev_i32_e32 v0, 6, v0
	v_lshrrev_b32_e32 v1, 26, v1
	s_or_b32 s11, s11, s14
	v_lshlrev_b32_e32 v3, 3, v0
	v_add_u32_e32 v1, v2, v1
	s_add_u32 s11, s0, s11
	v_and_b32_e32 v3, 0x7fff0, v3
	v_ashrrev_i32_e32 v1, 6, v1
	s_addc_u32 s14, s1, 0
	v_add_u32_e32 v3, v1, v3
	v_lshlrev_b32_e32 v0, 5, v0
	v_mul_i32_i24_e32 v1, 64, v1
	s_add_u32 s2, s11, s2
	v_and_b32_e32 v0, 32, v0
	v_sub_u32_e32 v1, v2, v1
	s_addc_u32 s3, s14, s3
	v_ashrrev_i16_sdwa v1, v174, sext(v1) dst_sel:DWORD dst_unused:UNUSED_PAD src0_sel:DWORD src1_sel:BYTE_0
	v_lshl_or_b32 v0, v3, 13, v0
	s_add_u32 s2, s2, 0x1deb0000
	v_add_u32_sdwa v152, v0, sext(v1) dst_sel:DWORD dst_unused:UNUSED_PAD src0_sel:DWORD src1_sel:WORD_0
	s_addc_u32 s3, s3, 0
	v_lshlrev_b64 v[0:1], 1, v[152:153]
	v_add_u32_e32 v14, s95, v16
	v_readlane_b32 s15, v255, 42
	v_lshl_add_u64 v[4:5], s[2:3], 0, v[0:1]
	v_readfirstlane_b32 s2, v14
	v_add_u32_e32 v15, 0x2000, v14
	s_mov_b32 m0, s2
	s_mov_b64 s[14:15], 0x100000
	v_readfirstlane_b32 s2, v15
	v_add_u32_e32 v12, 0, v16
	s_waitcnt lgkmcnt(0)
	s_barrier
	global_load_lds_dwordx4 v[4:5], off
	v_lshl_add_u64 v[2:3], v[4:5], 0, s[14:15]
	s_mov_b32 m0, s2
	v_readfirstlane_b32 s2, v12
	v_add_u32_e32 v13, 0x2000, v12
	global_load_lds_dwordx4 v[2:3], off
	v_lshl_add_u64 v[0:1], s[12:13], 0, v[0:1]
	s_mov_b32 m0, s2
	v_readfirstlane_b32 s2, v13
	v_add_u32_e32 v10, s28, v16
	global_load_lds_dwordx4 v[0:1], off
	v_lshl_add_u64 v[2:3], v[0:1], 0, s[14:15]
	s_mov_b32 m0, s2
	s_mov_b64 s[12:13], 0x200000
	v_readfirstlane_b32 s2, v10
	v_add_u32_e32 v11, 0x2000, v10
	global_load_lds_dwordx4 v[2:3], off
	v_lshl_add_u64 v[2:3], v[4:5], 0, s[12:13]
	s_mov_b32 m0, s2
	s_mov_b64 s[14:15], 0x300000
	v_readfirstlane_b32 s2, v11
	v_add_u32_e32 v8, 0x4000, v12
	global_load_lds_dwordx4 v[2:3], off
	v_lshl_add_u64 v[6:7], v[4:5], 0, s[14:15]
	s_mov_b32 m0, s2
	v_readfirstlane_b32 s2, v8
	v_add_u32_e32 v9, 0x6000, v12
	global_load_lds_dwordx4 v[6:7], off
	v_lshl_add_u64 v[6:7], v[0:1], 0, s[12:13]
	s_mov_b32 m0, s2
	v_readfirstlane_b32 s2, v9
	global_load_lds_dwordx4 v[6:7], off
	v_lshl_add_u64 v[18:19], v[0:1], 0, s[14:15]
	s_mov_b32 m0, s2
	v_ashrrev_i32_e32 v17, 8, v129
	global_load_lds_dwordx4 v[18:19], off
	v_cmp_eq_u32_e32 vcc, 1, v17
	v_readlane_b32 s18, v255, 45
	v_readlane_b32 s19, v255, 46
	s_and_saveexec_b64 s[2:3], vcc
	s_cbranch_execz .LBB0_394
	s_barrier

; DEV float logsig(float x) { return -log1pf(expf(-x)); }
; __device__ void job_retout_g(const P& p, int l, int job, HALF* sm) {
;     ...
;   const int nt2 = job & 1, h = (job >> 1) & 3, cgi = job >> 3;
;   const HALF* Qp = (const HALF*)(ws + G_Q) + (size_t)(cgi * 256) * 1024 + h * 256;
;   const float lgf = logsig(p.decay[l * 8 + h]);
;   const float lgb = logsig(p.decay[l * 8 + 4 + h]);
;   f4 acc[2][2][4][2];
;   zero_acc256(acc);
;   __syncthreads();
.LBB0_477:
	s_bfe_u32 s16, s14, 0x10002
	s_lshr_b32 s0, s14, 4
	s_lshl_b32 s0, s0, 1
	s_or_b32 s16, s16, s0
	s_lshl_b32 s0, s16, 8
	s_ashr_i32 s1, s0, 31
	s_mov_b64 s[2:3], s[20:21]
	s_and_b32 s17, s14, 3
	s_lshl_b64 s[8:9], s[0:1], 11
	s_add_u32 s6, s2, s8
	s_addc_u32 s7, s3, s9
	s_lshl_b32 s15, s17, 9
	s_add_u32 s12, s6, s15
	s_addc_u32 s13, s7, 0
	s_add_u32 s10, s12, 0x19eb0000
	v_readlane_b32 s6, v255, 54
	s_addc_u32 s11, s13, 0
	s_or_b32 s44, s17, s6
	v_readlane_b32 s68, v254, 14
	s_lshl_b64 s[6:7], s[44:45], 2
	v_readlane_b32 s74, v254, 20
	v_readlane_b32 s75, v254, 21
	s_add_u32 s6, s74, s6
	s_addc_u32 s7, s75, s7
	global_load_dword v0, v153, s[6:7]
	v_mov_b32_e32 v122, v155
	s_add_u32 s18, s2, 0x2beb0000
	s_addc_u32 s19, s3, 0
	s_lshl_b32 s20, s16, 2
	s_lshl_b32 s16, s14, 5
	v_readlane_b32 s70, v254, 16
	v_readlane_b32 s71, v254, 17
	s_and_b32 s16, s16, 0x100
	s_mov_b64 s[70:71], 0x20000
	v_readlane_b32 s69, v254, 15
	s_mov_b64 s[68:69], 0x20000
	v_readlane_b32 s72, v254, 18
	v_readlane_b32 s73, v254, 19
	v_readlane_b32 s76, v254, 22
	v_readlane_b32 s77, v254, 23
	v_readlane_b32 s78, v254, 24
	v_readlane_b32 s79, v254, 25
	v_readlane_b32 s80, v254, 26
	v_readlane_b32 s81, v254, 27
	v_readlane_b32 s82, v254, 28
	v_readlane_b32 s83, v254, 29
	s_waitcnt vmcnt(0)
	v_mul_f32_e32 v1, 0xbfb8aa3b, v0
	v_fma_f32 v2, v0, s31, -v1
	v_rndne_f32_e32 v3, v1
	v_fmac_f32_e32 v2, 0xb2a5705f, v0
	v_sub_f32_e32 v1, v1, v3
	v_add_f32_e32 v1, v1, v2
	v_exp_f32_e32 v1, v1
	v_cvt_i32_f32_e32 v2, v3
	v_cmp_nlt_f32_e32 vcc, s34, v0
	v_ldexp_f32 v1, v1, v2
	s_nop 0
	v_cndmask_b32_e32 v1, 0, v1, vcc
	v_cmp_ngt_f32_e32 vcc, s35, v0
	s_nop 1
	v_cndmask_b32_e32 v120, v181, v1, vcc
	v_add_f32_e32 v2, 1.0, v120
	v_add_f32_e32 v0, -1.0, v2
	v_sub_f32_e32 v1, v0, v2
	v_add_f32_e32 v1, 1.0, v1
	v_sub_f32_e32 v0, v120, v0
	v_add_f32_e32 v3, v0, v1
	v_cvt_f64_f32_e32 v[0:1], v2
	v_frexp_exp_i32_f64_e32 v5, v[0:1]
	global_load_dword v0, v153, s[6:7] offset:16
	v_frexp_mant_f32_e32 v4, v2
	s_mov_b32 s6, 0x3f2aaaab
	s_waitcnt vmcnt(0)
; DEV int opaque_tid512() { int t = threadIdx.x; asm volatile("" : "+v"(t)); return t; }
; DEV float logsig(float x) { return -log1pf(expf(-x)); }
;   #define STAGE(P,BASE,LD,br,kt) do{ const HALF* _u=(BASE)+(long)(br)*(((&(LD))==&lda)?lda_u:(LD))+(long)(kt)*G_BK; \
;     for(int _i=0;_i<2;++_i){ \
;       __builtin_amdgcn_global_load_lds((const unsigned*)(_u+(long)_i*(((&(LD))==&lda)?stepa:stepb)+((&(LD))==&lda?oa0:ob0)), \
;         (unsigned*)((char*)(P)+t5*16+_i*8192),16,0,0);}}while(0)
;   #define BAR __builtin_amdgcn_s_barrier()
;     ...
;   const int t5=opaque_tid512();
;   const int wid=t5>>6,lane=t5&63,wr=wid>>2,wc=wid&3,fr=lane&15,fq=lane>>4;
;   h8 At[4][2],B0[2][2],B1[2][2];
;   const int nt=K/G_BK;
;   const int _ob=fr*64+fq*16, _sw=_ob^(((_ob>>9)&1)<<5);
;   const char* la=(const char*)shm+wr*8192+_sw;
;   const char* lb=(const char*)shm+65536+wc*4096+_sw;
;   unsigned oa0, ob0;
;   const int stepa = n2 ? 1024 : 64 * lda, stepb = 64 * ldb;
;   const int lda_u = n2 ? 16 : lda;
;   {int _b=t5*16;int _r,_c;g_stage_rc(_b,_r,_c);
;     oa0=n2 ? (unsigned)((n2*(_r&63)+(_r>>6))*1024+_c) : (unsigned)(_r*lda+_c); ob0=(unsigned)(_r*ldb+_c);}
;   STAGE(SB(0,0),Bt,ldb,0,0); STAGE(SA(0,0),A,lda,0,0);
;   STAGE(SB(0,1),Bt,ldb,G_HALF,0); STAGE(SA(0,1),A,lda,G_HALF,0);
;   if(wr==1)BAR;
; __device__ void job_retout_g(const P& p, int l, int job, HALF* sm) {
;     ...
;   const float lgf = logsig(p.decay[l * 8 + h]);
;   const float lgb = logsig(p.decay[l * 8 + 4 + h]);
;   f4 acc[2][2][4][2];
;   zero_acc256(acc);
;   __syncthreads();
;   {
;     const HALF* Sf = (const HALF*)(ws + G_ST) + ((size_t)((0 * 32 + cgi) * 4 + h) * 512 + nt2 * 256) * 256;
;     gemm256(acc, Sf, 256, Qp, 1024, 256, sm);
	v_mul_f32_e32 v1, 0xbfb8aa3b, v0
	v_fma_f32 v6, v0, s31, -v1
	v_rndne_f32_e32 v7, v1
	v_fmac_f32_e32 v6, 0xb2a5705f, v0
	v_sub_f32_e32 v1, v1, v7
	v_add_f32_e32 v1, v1, v6
	v_exp_f32_e32 v1, v1
	v_cvt_i32_f32_e32 v6, v7
	v_cmp_nlt_f32_e32 vcc, s34, v0
	v_ldexp_f32 v1, v1, v6
	s_nop 0
	v_cndmask_b32_e32 v1, 0, v1, vcc
	v_cmp_ngt_f32_e32 vcc, s35, v0
	s_nop 1
	v_cndmask_b32_e32 v121, v181, v1, vcc
	v_add_f32_e32 v6, 1.0, v121
	v_add_f32_e32 v0, -1.0, v6
	v_sub_f32_e32 v1, v0, v6
	v_add_f32_e32 v1, 1.0, v1
	v_sub_f32_e32 v0, v121, v0
	v_add_f32_e32 v7, v0, v1
	v_frexp_mant_f32_e32 v8, v6
	v_cvt_f64_f32_e32 v[0:1], v6
	v_cmp_gt_f32_e32 vcc, s6, v4
	v_frexp_exp_i32_f64_e32 v0, v[0:1]
	v_cmp_gt_f32_e64 s[6:7], s6, v8
	v_subbrev_co_u32_e32 v21, vcc, 0, v5, vcc
	s_nop 0
	v_subbrev_co_u32_e64 v20, s[6:7], 0, v0, s[6:7]
	v_sub_u32_e32 v0, 0, v21
	v_ldexp_f32 v1, v2, v0
	v_sub_u32_e32 v2, 0, v20
	v_ldexp_f32 v3, v3, v0
	v_ldexp_f32 v0, v6, v2
	v_pk_add_f32 v[4:5], v[0:1], 1.0 op_sel_hi:[1,0]
	v_ldexp_f32 v2, v7, v2
	v_pk_add_f32 v[6:7], v[4:5], -1.0 op_sel_hi:[1,0]
	v_pk_add_f32 v[12:13], v[0:1], -1.0 op_sel_hi:[1,0]
	v_pk_add_f32 v[6:7], v[0:1], v[6:7] neg_lo:[0,1] neg_hi:[0,1]
	v_pk_add_f32 v[14:15], v[12:13], 1.0 op_sel_hi:[1,0]
	v_pk_add_f32 v[6:7], v[2:3], v[6:7]
	v_pk_add_f32 v[0:1], v[0:1], v[14:15] neg_lo:[0,1] neg_hi:[0,1]
	v_pk_add_f32 v[8:9], v[4:5], v[6:7]
	v_pk_add_f32 v[0:1], v[2:3], v[0:1]
	v_rcp_f32_e32 v11, v9
	v_rcp_f32_e32 v10, v8
	v_pk_add_f32 v[2:3], v[12:13], v[0:1]
	v_pk_add_f32 v[4:5], v[4:5], v[8:9] neg_lo:[0,1] neg_hi:[0,1]
	v_pk_add_f32 v[12:13], v[12:13], v[2:3] neg_lo:[0,1] neg_hi:[0,1]
	v_pk_add_f32 v[4:5], v[6:7], v[4:5]
	v_pk_mul_f32 v[6:7], v[2:3], v[10:11]
	v_pk_add_f32 v[0:1], v[0:1], v[12:13]
	v_pk_mul_f32 v[12:13], v[8:9], v[6:7]
	v_cvt_f32_i32_e32 v81, v21
	v_pk_fma_f32 v[14:15], v[6:7], v[8:9], v[12:13] neg_lo:[0,0,1] neg_hi:[0,0,1]
	v_cvt_f32_i32_e32 v80, v20
	v_pk_fma_f32 v[14:15], v[6:7], v[4:5], v[14:15]
	s_mov_b32 s6, 0x3e9b6dac
	v_pk_add_f32 v[16:17], v[12:13], v[14:15]
	s_nop 0
	v_pk_add_f32 v[18:19], v[2:3], v[16:17] neg_lo:[0,1] neg_hi:[0,1]
	v_pk_add_f32 v[12:13], v[16:17], v[12:13] neg_lo:[0,1] neg_hi:[0,1]
	v_pk_add_f32 v[2:3], v[2:3], v[18:19] neg_lo:[0,1] neg_hi:[0,1]
	s_nop 0
	v_pk_add_f32 v[2:3], v[2:3], v[16:17] neg_lo:[0,1] neg_hi:[0,1]
	s_nop 0
	v_pk_add_f32 v[0:1], v[0:1], v[2:3]
	v_pk_add_f32 v[2:3], v[12:13], v[14:15] neg_lo:[0,1] neg_hi:[0,1]
	s_nop 0
	v_pk_add_f32 v[0:1], v[2:3], v[0:1]
	s_nop 0
	v_pk_add_f32 v[2:3], v[18:19], v[0:1]
	s_nop 0
	v_pk_mul_f32 v[12:13], v[10:11], v[2:3]
	s_nop 0
	v_pk_mul_f32 v[14:15], v[8:9], v[12:13]
	v_pk_add_f32 v[74:75], v[6:7], v[12:13]
	v_pk_fma_f32 v[8:9], v[12:13], v[8:9], v[14:15] neg_lo:[0,0,1] neg_hi:[0,0,1]
	s_nop 0
	v_pk_fma_f32 v[4:5], v[12:13], v[4:5], v[8:9]
	v_pk_add_f32 v[8:9], v[18:19], v[2:3] neg_lo:[0,1] neg_hi:[0,1]
	s_nop 0
	v_pk_add_f32 v[0:1], v[0:1], v[8:9]
	v_pk_add_f32 v[8:9], v[14:15], v[4:5]
	s_nop 0
	v_pk_add_f32 v[16:17], v[2:3], v[8:9] neg_lo:[0,1] neg_hi:[0,1]
	v_pk_add_f32 v[14:15], v[8:9], v[14:15] neg_lo:[0,1] neg_hi:[0,1]
	v_pk_add_f32 v[2:3], v[2:3], v[16:17] neg_lo:[0,1] neg_hi:[0,1]
	s_nop 0
	v_pk_add_f32 v[2:3], v[2:3], v[8:9] neg_lo:[0,1] neg_hi:[0,1]
	s_nop 0
	v_pk_add_f32 v[0:1], v[0:1], v[2:3]
	v_pk_add_f32 v[2:3], v[14:15], v[4:5] neg_lo:[0,1] neg_hi:[0,1]
	v_bfe_i32 v5, v122, 27, 1
	v_pk_add_f32 v[0:1], v[2:3], v[0:1]
	v_pk_add_f32 v[2:3], v[74:75], v[6:7] neg_lo:[0,1] neg_hi:[0,1]
	v_lshrrev_b32_e32 v5, 22, v5
	v_pk_add_f32 v[2:3], v[12:13], v[2:3] neg_lo:[0,1] neg_hi:[0,1]
	v_lshlrev_b32_e32 v12, 4, v122
	v_add_u32_e32 v5, v12, v5
	v_and_b32_e32 v5, 0xfffffc00, v5
	v_ashrrev_i32_e32 v4, 31, v122
	v_sub_u32_e32 v5, v12, v5
	v_lshrrev_b32_e32 v4, 26, v4
	v_lshrrev_b32_e32 v6, 4, v5
	v_pk_add_f32 v[0:1], v[16:17], v[0:1]
	v_add_u32_e32 v4, v122, v4
	v_bitop3_b32 v6, v6, v5, 32 bitop3:0x6c
	v_ashrrev_i32_e32 v5, 31, v5
	v_pk_mul_f32 v[0:1], v[10:11], v[0:1]
	v_ashrrev_i32_e32 v4, 6, v4
	v_lshrrev_b32_e32 v5, 26, v5
	v_pk_add_f32 v[90:91], v[2:3], v[0:1]
	v_lshlrev_b32_e32 v7, 3, v4
	v_add_u32_e32 v5, v6, v5
	v_pk_add_f32 v[82:83], v[74:75], v[90:91]
	v_and_b32_e32 v7, -16, v7
	v_ashrrev_i32_e32 v5, 6, v5
	v_pk_mul_f32 v[88:89], v[82:83], v[82:83]
	v_add_u32_e32 v10, v5, v7
	v_mul_i32_i24_e32 v5, 64, v5
	v_pk_fma_f32 v[0:1], v[88:89], s[6:7], v[154:155] op_sel_hi:[1,0,0]
	s_mov_b32 s6, 0x3f317218
	v_sub_u32_e32 v5, v6, v5
	v_pk_mul_f32 v[72:73], v[80:81], s[6:7] op_sel_hi:[1,0]
	v_lshlrev_b32_e32 v4, 5, v4
	v_ashrrev_i16_sdwa v5, v174, sext(v5) dst_sel:DWORD dst_unused:UNUSED_PAD src0_sel:DWORD src1_sel:BYTE_0
	v_pk_fma_f32 v[2:3], v[80:81], s[6:7], v[72:73] op_sel_hi:[1,0,1] neg_lo:[0,0,1] neg_hi:[0,0,1]
	s_or_b32 s6, s20, s17
	v_and_b32_e32 v4, 32, v4
	v_bfe_i32 v5, v5, 0, 16
	v_lshlrev_b32_e32 v6, 10, v10
	s_ashr_i32 s7, s6, 31
	v_add3_u32 v152, v4, v5, v6
	v_add_u32_e32 v13, s95, v12
	s_lshl_b64 s[6:7], s[6:7], 18
	v_lshlrev_b64 v[8:9], 1, v[152:153]
	v_readfirstlane_b32 s22, v13
	v_add_u32_e32 v15, 0x2000, v13
	s_add_u32 s6, s18, s6
	v_lshl_add_u64 v[4:5], s[10:11], 0, v[8:9]
	s_mov_b32 m0, s22
	v_readfirstlane_b32 s22, v15
	s_addc_u32 s7, s19, s7
	s_lshl_b32 s21, s16, 9
	s_barrier
	global_load_lds_dwordx4 v[4:5], off
	v_lshl_add_u64 v[6:7], v[4:5], 0, s[70:71]
	s_mov_b32 m0, s22
	s_movk_i32 s22, 0xfd00
	s_add_u32 s6, s6, s21
	global_load_lds_dwordx4 v[6:7], off
	v_mad_u64_u32 v[6:7], s[58:59], v10, s22, v[152:153]
	s_addc_u32 s7, s7, 0
	v_mov_b32_e32 v7, v153
	v_add_u32_e32 v20, 0, v12
	v_lshl_add_u64 v[6:7], v[6:7], 1, s[6:7]
	v_readfirstlane_b32 s6, v20
	s_mov_b32 m0, s6
	s_mov_b64 s[6:7], 0x8000
	v_add_u32_e32 v21, 0x2000, v20
	v_lshl_add_u64 v[10:11], v[6:7], 0, s[6:7]
	v_readfirstlane_b32 s6, v21
	s_add_u32 s58, s12, 0x19ef0000
	v_add_u32_e32 v18, s28, v12
	global_load_lds_dwordx4 v[6:7], off
	s_mov_b32 m0, s6
	s_addc_u32 s59, s13, 0
	v_readfirstlane_b32 s6, v18
	v_add_u32_e32 v19, 0x2000, v18
	global_load_lds_dwordx4 v[10:11], off
	v_lshl_add_u64 v[8:9], s[58:59], 0, v[8:9]
	s_mov_b32 m0, s6
	v_readfirstlane_b32 s6, v19
	global_load_lds_dwordx4 v[8:9], off
	v_lshl_add_u64 v[10:11], v[8:9], 0, s[70:71]
	s_mov_b32 m0, s6
	s_mov_b64 s[6:7], 0x10000
	v_add_u32_e32 v16, 0x4000, v20
	global_load_lds_dwordx4 v[10:11], off
	v_lshl_add_u64 v[10:11], v[6:7], 0, s[6:7]
	v_readfirstlane_b32 s6, v16
	s_mov_b32 m0, s6
	s_mov_b64 s[6:7], 0x18000
	v_add_u32_e32 v17, 0x6000, v20
	v_lshl_add_u64 v[22:23], v[6:7], 0, s[6:7]
	v_readfirstlane_b32 s6, v17
	global_load_lds_dwordx4 v[10:11], off
	s_mov_b32 m0, s6
	v_ashrrev_i32_e32 v14, 8, v122
	global_load_lds_dwordx4 v[22:23], off
	v_cmp_eq_u32_e32 vcc, 1, v14
	s_and_saveexec_b64 s[6:7], vcc
	s_cbranch_execz .LBB0_479
	s_barrier

; DEV float logsig(float x) { return -log1pf(expf(-x)); }
; __device__ void job_retout_g(const P& p, int l, int job, HALF* sm) {
;     ...
;   const float lgf = logsig(p.decay[l * 8 + h]);
;   const float lgb = logsig(p.decay[l * 8 + 4 + h]);
;     ...
;   __syncthreads();
;   {
;     const HALF* Sb = (const HALF*)(ws + G_ST) + ((size_t)((1 * 32 + cgi) * 4 + h) * 512 + nt2 * 256) * 256;
;     gemm256(acc, Sb, 256, Qp, 1024, 256, sm);
.LBB0_481:
	s_or_b64 exec, exec, s[12:13]
	v_pk_add_f32 v[74:75], v[82:83], v[74:75] neg_lo:[0,1] neg_hi:[0,1]
	v_ldexp_f32 v122, v82, 1
	v_pk_add_f32 v[74:75], v[90:91], v[74:75] neg_lo:[0,1] neg_hi:[0,1]
	v_ldexp_f32 v91, v83, 1
	v_pk_mul_f32 v[82:83], v[82:83], v[88:89]
	v_mov_b32_e32 v157, v95
	v_mov_b32_e32 v81, v83
	v_pk_mul_f32 v[80:81], v[80:81], v[156:157]
	v_pk_mul_f32 v[82:83], v[82:83], v[94:95]
	v_mov_b32_e32 v90, v92
	v_mov_b32_e32 v123, v91
	v_pk_add_f32 v[80:81], v[80:81], v[90:91]
	v_pk_add_f32 v[90:91], v[122:123], v[82:83]
	v_ldexp_f32 v75, v75, 1
	v_pk_add_f32 v[94:95], v[90:91], v[122:123] neg_lo:[0,1] neg_hi:[0,1]
	v_ldexp_f32 v124, v74, 1
	v_pk_add_f32 v[82:83], v[82:83], v[94:95] neg_lo:[0,1] neg_hi:[0,1]
	v_mov_b32_e32 v125, v75
	v_mov_b32_e32 v94, v72
	v_mov_b32_e32 v95, v83
	v_mov_b32_e32 v74, v92
	v_pk_add_f32 v[122:123], v[124:125], v[82:83]
	v_pk_add_f32 v[94:95], v[94:95], v[74:75]
	v_mov_b32_e32 v74, v90
	v_mov_b32_e32 v82, v122
	v_pk_add_f32 v[88:89], v[72:73], v[92:93]
	v_pk_add_f32 v[74:75], v[74:75], v[82:83]
	v_pk_add_f32 v[82:83], v[90:91], v[122:123]
	v_mov_b32_e32 v124, v88
	v_mov_b32_e32 v125, v73
	v_mov_b32_e32 v126, v82
	v_mov_b32_e32 v127, v93
	v_pk_add_f32 v[74:75], v[80:81], v[74:75]
	v_pk_add_f32 v[80:81], v[88:89], v[82:83]
	v_pk_add_f32 v[158:159], v[124:125], v[126:127]
	v_mov_b32_e32 v160, v82
	v_mov_b32_e32 v161, v81
	v_mov_b32_e32 v162, v90
	v_mov_b32_e32 v163, v89
	v_pk_add_f32 v[160:161], v[160:161], v[162:163] neg_lo:[0,1] neg_hi:[0,1]
	v_mov_b32_e32 v164, v72
	v_pk_add_f32 v[72:73], v[88:89], v[72:73] neg_lo:[0,1] neg_hi:[0,1]
	v_pk_add_f32 v[124:125], v[158:159], v[124:125] neg_lo:[0,1] neg_hi:[0,1]
	v_mov_b32_e32 v162, v88
	v_mov_b32_e32 v163, v81
	v_mov_b32_e32 v165, v161
	v_mov_b32_e32 v88, v92
	v_pk_add_f32 v[72:73], v[92:93], v[72:73] neg_lo:[0,1] neg_hi:[0,1]
	v_pk_add_f32 v[92:93], v[82:83], v[90:91] neg_lo:[0,1] neg_hi:[0,1]
	v_mov_b32_e32 v90, v124
	v_pk_add_f32 v[162:163], v[162:163], v[164:165] neg_lo:[0,1] neg_hi:[0,1]
	v_mov_b32_e32 v82, v122
	v_pk_add_f32 v[74:75], v[74:75], v[90:91] neg_lo:[0,1] neg_hi:[0,1]
	v_pk_add_f32 v[88:89], v[88:89], v[162:163] neg_lo:[0,1] neg_hi:[0,1]
	v_pk_add_f32 v[82:83], v[82:83], v[160:161] neg_lo:[0,1] neg_hi:[0,1]
	v_pk_add_f32 v[74:75], v[94:95], v[74:75] neg_lo:[0,1] neg_hi:[0,1]
	v_pk_add_f32 v[90:91], v[122:123], v[92:93] neg_lo:[0,1] neg_hi:[0,1]
	v_pk_add_f32 v[92:93], v[126:127], v[124:125] neg_lo:[0,1] neg_hi:[0,1]
	v_pk_add_f32 v[122:123], v[82:83], v[88:89]
	v_mov_b32_e32 v83, v75
	v_pk_add_f32 v[94:95], v[92:93], v[74:75]
	v_pk_add_f32 v[72:73], v[72:73], v[82:83]
	v_mov_b32_e32 v89, v93
	v_pk_add_f32 v[72:73], v[72:73], v[88:89] neg_lo:[0,1] neg_hi:[0,1]
	v_mov_b32_e32 v74, v122
	v_mov_b32_e32 v75, v95
	v_pk_add_f32 v[74:75], v[74:75], v[72:73] neg_lo:[0,1] neg_hi:[0,1]
	v_pk_add_f32 v[72:73], v[90:91], v[72:73] neg_lo:[0,1] neg_hi:[0,1]
	v_pk_add_f32 v[74:75], v[88:89], v[74:75] neg_lo:[0,1] neg_hi:[0,1]
	s_mov_b32 s12, 0x7f800000
	v_pk_add_f32 v[72:73], v[72:73], v[74:75]
	v_pk_add_f32 v[74:75], v[94:95], v[122:123]
	v_cmp_neq_f32_e32 vcc, s12, v121
	v_pk_add_f32 v[82:83], v[80:81], v[74:75]
	v_and_b32_e32 v152, 0x7fffffff, v120
	v_pk_add_f32 v[80:81], v[82:83], v[80:81] neg_lo:[0,1] neg_hi:[0,1]
	v_and_b32_e32 v166, 0x7fffffff, v121
	v_pk_add_f32 v[74:75], v[74:75], v[80:81] neg_lo:[0,1] neg_hi:[0,1]
	v_mov_b32_e32 v157, v155
	v_pk_add_f32 v[72:73], v[72:73], v[74:75]
	s_nop 0
	v_pk_add_f32 v[72:73], v[82:83], v[72:73]
	s_nop 0
	v_cndmask_b32_e32 v72, v181, v72, vcc
	v_cmp_neq_f32_e32 vcc, s12, v120
	s_mov_b32 s12, 0x33800000
	s_nop 0
	v_cndmask_b32_e32 v73, v181, v73, vcc
	v_cmp_gt_f32_e32 vcc, s12, v152
	s_nop 1
	v_cndmask_b32_e32 v159, v73, v120, vcc
	v_cmp_gt_f32_e32 vcc, s12, v166
	s_movk_i32 s12, 0x60
	s_nop 0
	v_cndmask_b32_e32 v158, v72, v121, vcc
	v_mov_b32_e32 v72, v155
	v_and_b32_e32 v73, 15, v72
	v_bfe_i32 v74, v157, 27, 1
	v_lshlrev_b32_e32 v194, 4, v157
	v_lshrrev_b32_e32 v74, 22, v74
	v_add_u32_e32 v74, v194, v74
	v_lshrrev_b32_e32 v72, 1, v72
	v_and_b32_e32 v74, 0xfffffc00, v74
	v_and_or_b32 v82, v72, s12, v73
	v_ashrrev_i32_e32 v73, 31, v157
	v_sub_u32_e32 v74, v194, v74
	v_lshrrev_b32_e32 v73, 26, v73
	v_lshrrev_b32_e32 v75, 4, v74
	v_add_u32_e32 v73, v157, v73
	v_bitop3_b32 v75, v75, v74, 32 bitop3:0x6c
	v_ashrrev_i32_e32 v74, 31, v74
	v_ashrrev_i32_e32 v73, 6, v73
	v_lshrrev_b32_e32 v74, 26, v74
	v_lshlrev_b32_e32 v80, 3, v73
	v_add_u32_e32 v74, v75, v74
	v_and_b32_e32 v80, -16, v80
	v_ashrrev_i32_e32 v74, 6, v74
	v_add_u32_e32 v83, v74, v80
	v_mul_i32_i24_e32 v74, 64, v74
	v_sub_u32_e32 v74, v75, v74
	s_add_i32 s12, s20, s17
	v_lshlrev_b32_e32 v73, 5, v73
	v_ashrrev_i16_sdwa v74, v174, sext(v74) dst_sel:DWORD dst_unused:UNUSED_PAD src0_sel:DWORD src1_sel:BYTE_0
	s_addk_i32 s12, 0x80
	v_and_b32_e32 v73, 32, v73
	v_bfe_i32 v74, v74, 0, 16
	v_lshlrev_b32_e32 v75, 10, v83
	s_ashr_i32 s13, s12, 31
	v_add3_u32 v152, v73, v74, v75
	s_lshl_b64 s[12:13], s[12:13], 18
	v_lshlrev_b64 v[74:75], 1, v[152:153]
	v_add_u32_e32 v192, s95, v194
	s_add_u32 s12, s18, s12
	v_lshl_add_u64 v[164:165], s[10:11], 0, v[74:75]
	v_readfirstlane_b32 s10, v192
	v_add_u32_e32 v193, 0x2000, v192
	s_addc_u32 s13, s19, s13
	s_mov_b32 m0, s10
	s_mov_b64 s[18:19], 0x20000
	v_readfirstlane_b32 s10, v193
	s_waitcnt vmcnt(0)
	s_barrier
; DEV int opaque_tid512() { int t = threadIdx.x; asm volatile("" : "+v"(t)); return t; }
;   #define STAGE(P,BASE,LD,br,kt) do{ const HALF* _u=(BASE)+(long)(br)*(((&(LD))==&lda)?lda_u:(LD))+(long)(kt)*G_BK; \
;     for(int _i=0;_i<2;++_i){ \
;       __builtin_amdgcn_global_load_lds((const unsigned*)(_u+(long)_i*(((&(LD))==&lda)?stepa:stepb)+((&(LD))==&lda?oa0:ob0)), \
;         (unsigned*)((char*)(P)+t5*16+_i*8192),16,0,0);}}while(0)
;   #define BAR __builtin_amdgcn_s_barrier()
; #define FOR_AI _Pragma("unroll") for (int ai = 0; ai < 2; ++ai)
; #define FOR_BJ _Pragma("unroll") for (int bj = 0; bj < 2; ++bj)
; #define FOR_M4 _Pragma("unroll") for (int m = 0; m < 4; ++m)
; #define FOR_NN _Pragma("unroll") for (int n = 0; n < 2; ++n)
;     ...
;   const int t5=opaque_tid512();
;   const int wid=t5>>6,lane=t5&63,wr=wid>>2,wc=wid&3,fr=lane&15,fq=lane>>4;
;   h8 At[4][2],B0[2][2],B1[2][2];
;   const int nt=K/G_BK;
;   const int _ob=fr*64+fq*16, _sw=_ob^(((_ob>>9)&1)<<5);
;   const char* la=(const char*)shm+wr*8192+_sw;
;   const char* lb=(const char*)shm+65536+wc*4096+_sw;
;   unsigned oa0, ob0;
;   const int stepa = n2 ? 1024 : 64 * lda, stepb = 64 * ldb;
;   const int lda_u = n2 ? 16 : lda;
;   {int _b=t5*16;int _r,_c;g_stage_rc(_b,_r,_c);
;     oa0=n2 ? (unsigned)((n2*(_r&63)+(_r>>6))*1024+_c) : (unsigned)(_r*lda+_c); ob0=(unsigned)(_r*ldb+_c);}
;   STAGE(SB(0,0),Bt,ldb,0,0); STAGE(SA(0,0),A,lda,0,0);
;   STAGE(SB(0,1),Bt,ldb,G_HALF,0); STAGE(SA(0,1),A,lda,G_HALF,0);
;   if(wr==1)BAR;
; __device__ void job_retout_g(const P& p, int l, int job, HALF* sm) {
;     ...
;     IDS8_FRESH
;     FOR_BJ FOR_NN {
;       const int i = bj * 128 + wc * 32 + n * 16 + fr;
;       const float sc = expf(lgf * (float)(i + 1) - lgb * (float)(256 - i));
;       FOR_AI FOR_M4 { acc[ai][bj][m][n] *= sc; }
;     }
;   }
	global_load_lds_dwordx4 v[164:165], off
	v_lshl_add_u64 v[80:81], v[164:165], 0, s[18:19]
	s_mov_b32 m0, s10
	s_movk_i32 s10, 0xfd00
	s_add_u32 s12, s12, s21
	global_load_lds_dwordx4 v[80:81], off
	v_mad_u64_u32 v[80:81], s[10:11], v83, s10, v[152:153]
	v_add_u32_e32 v190, 0, v194
	s_addc_u32 s13, s13, 0
	v_mov_b32_e32 v81, v153
	v_readfirstlane_b32 s10, v190
	v_lshl_add_u64 v[160:161], v[80:81], 1, s[12:13]
	s_mov_b32 m0, s10
	s_mov_b64 s[10:11], 0x8000
	v_add_u32_e32 v191, 0x2000, v190
	v_lshl_add_u64 v[80:81], v[160:161], 0, s[10:11]
	v_readfirstlane_b32 s10, v191
	v_add_u32_e32 v188, s28, v194
	global_load_lds_dwordx4 v[160:161], off
	s_mov_b32 m0, s10
	v_readfirstlane_b32 s10, v188
	v_add_u32_e32 v189, 0x2000, v188
	global_load_lds_dwordx4 v[80:81], off
	v_lshl_add_u64 v[162:163], s[58:59], 0, v[74:75]
	s_mov_b32 m0, s10
	v_readfirstlane_b32 s10, v189
	global_load_lds_dwordx4 v[162:163], off
	s_mov_b32 m0, s10
	s_mov_b64 s[10:11], 0x10000
	v_add_u32_e32 v186, 0x4000, v190
	v_lshl_add_u64 v[74:75], v[162:163], 0, s[18:19]
	v_lshl_add_u64 v[166:167], v[160:161], 0, s[10:11]
	v_readfirstlane_b32 s10, v186
	global_load_lds_dwordx4 v[74:75], off
	s_mov_b32 m0, s10
	s_mov_b64 s[10:11], 0x18000
	v_add_u32_e32 v187, 0x6000, v190
	v_lshl_add_u64 v[74:75], v[160:161], 0, s[10:11]
	v_readfirstlane_b32 s10, v187
	global_load_lds_dwordx4 v[166:167], off
	s_mov_b32 m0, s10
	v_sub_u32_e32 v72, 0x100, v82
	global_load_lds_dwordx4 v[74:75], off
	v_cvt_f32_u32_e32 v72, v72
	v_add_u32_e32 v73, 1, v82
	v_cvt_f32_ubyte0_e32 v73, v73
	v_pk_mul_f32 v[72:73], v[158:159], v[72:73]
	s_nop 0
	v_sub_f32_e32 v74, v72, v73
	v_mul_f32_e32 v72, 0x3fb8aa3b, v74
	v_fma_f32 v73, v74, s30, -v72
	v_rndne_f32_e32 v75, v72
	v_fmac_f32_e32 v73, 0x32a5705f, v74
	v_sub_f32_e32 v72, v72, v75
	v_add_f32_e32 v72, v72, v73
	v_exp_f32_e32 v72, v72
	v_cvt_i32_f32_e32 v73, v75
	v_cmp_ngt_f32_e32 vcc, s33, v74
	v_ldexp_f32 v75, v72, v73
	v_sub_u32_e32 v72, 0xf0, v82
	v_add_u32_e32 v73, 17, v82
	v_cvt_f32_ubyte0_e32 v73, v73
	v_cvt_f32_ubyte0_e32 v72, v72
	v_pk_mul_f32 v[72:73], v[158:159], v[72:73]
	v_cndmask_b32_e32 v75, 0, v75, vcc
	v_sub_f32_e32 v80, v72, v73
	v_mul_f32_e32 v72, 0x3fb8aa3b, v80
	v_fma_f32 v73, v80, s30, -v72
	v_rndne_f32_e32 v81, v72
	v_fmac_f32_e32 v73, 0x32a5705f, v80
	v_sub_f32_e32 v72, v72, v81
	v_add_f32_e32 v72, v72, v73
	v_exp_f32_e32 v72, v72
	v_cvt_i32_f32_e32 v73, v81
	v_cmp_nlt_f32_e32 vcc, s86, v74
	v_ldexp_f32 v72, v72, v73
	s_nop 0
	v_cndmask_b32_e32 v120, v181, v75, vcc
	v_cmp_ngt_f32_e32 vcc, s33, v80
	v_add_u32_e32 v73, 0x81, v82
	v_cvt_f32_ubyte0_e32 v73, v73
	v_cndmask_b32_e32 v74, 0, v72, vcc
	v_sub_u32_e32 v72, 0x80, v82
	v_cvt_f32_ubyte0_e32 v72, v72
	v_pk_mul_f32 v[72:73], v[158:159], v[72:73]
	v_cmp_nlt_f32_e32 vcc, s86, v80
	v_sub_f32_e32 v75, v72, v73
	v_mul_f32_e32 v72, 0x3fb8aa3b, v75
	v_fma_f32 v73, v75, s30, -v72
	v_rndne_f32_e32 v81, v72
	v_fmac_f32_e32 v73, 0x32a5705f, v75
	v_sub_f32_e32 v72, v72, v81
	v_add_f32_e32 v72, v72, v73
	v_exp_f32_e32 v72, v72
	v_cvt_i32_f32_e32 v81, v81
	v_add_u32_e32 v73, 0x91, v82
	v_cvt_f32_u32_e32 v73, v73
	v_cndmask_b32_e32 v170, v181, v74, vcc
	v_ldexp_f32 v74, v72, v81
	v_sub_u32_e32 v72, 0x70, v82
	v_cvt_f32_ubyte0_e32 v72, v72
	v_pk_mul_f32 v[72:73], v[158:159], v[72:73]
	v_cmp_ngt_f32_e32 vcc, s33, v75
	v_sub_f32_e32 v72, v72, v73
	v_mul_f32_e32 v73, 0x3fb8aa3b, v72
	v_fma_f32 v80, v72, s30, -v73
	v_rndne_f32_e32 v81, v73
	v_fmac_f32_e32 v80, 0x32a5705f, v72
	v_sub_f32_e32 v73, v73, v81
	v_add_f32_e32 v73, v73, v80
	v_exp_f32_e32 v73, v73
	v_cvt_i32_f32_e32 v80, v81
	v_cndmask_b32_e32 v74, 0, v74, vcc
	v_cmp_nlt_f32_e32 vcc, s86, v75
	v_ashrrev_i32_e32 v159, 8, v157
	v_ldexp_f32 v73, v73, v80
	v_cndmask_b32_e32 v172, v181, v74, vcc
	v_cmp_ngt_f32_e32 vcc, s33, v72
	s_nop 1
	v_cndmask_b32_e32 v73, 0, v73, vcc
	v_cmp_nlt_f32_e32 vcc, s86, v72
	s_nop 1
	v_cndmask_b32_e32 v168, v181, v73, vcc
	v_cmp_eq_u32_e32 vcc, 1, v159
	s_and_saveexec_b64 s[10:11], vcc
	s_cbranch_execz .LBB0_483
	s_barrier

; DEV int opaque_tid512() { int t = threadIdx.x; asm volatile("" : "+v"(t)); return t; }
;   #define STAGE(P,BASE,LD,br,kt) do{ const HALF* _u=(BASE)+(long)(br)*(((&(LD))==&lda)?lda_u:(LD))+(long)(kt)*G_BK; \
;     for(int _i=0;_i<2;++_i){ \
;       __builtin_amdgcn_global_load_lds((const unsigned*)(_u+(long)_i*(((&(LD))==&lda)?stepa:stepb)+((&(LD))==&lda?oa0:ob0)), \
;         (unsigned*)((char*)(P)+t5*16+_i*8192),16,0,0);}}while(0)
;   #define BAR __builtin_amdgcn_s_barrier()
; #define FOR_AI _Pragma("unroll") for (int ai = 0; ai < 2; ++ai)
; #define FOR_BJ _Pragma("unroll") for (int bj = 0; bj < 2; ++bj)
; #define FOR_M4 _Pragma("unroll") for (int m = 0; m < 4; ++m)
; #define FOR_NN _Pragma("unroll") for (int n = 0; n < 2; ++n)
;     ...
;   const int t5=opaque_tid512();
;   const int wid=t5>>6,lane=t5&63,wr=wid>>2,wc=wid&3,fr=lane&15,fq=lane>>4;
;   h8 At[4][2],B0[2][2],B1[2][2];
;   const int nt=K/G_BK;
;   const int _ob=fr*64+fq*16, _sw=_ob^(((_ob>>9)&1)<<5);
;   const char* la=(const char*)shm+wr*8192+_sw;
;   const char* lb=(const char*)shm+65536+wc*4096+_sw;
;   unsigned oa0, ob0;
;   const int stepa = n2 ? 1024 : 64 * lda, stepb = 64 * ldb;
;   const int lda_u = n2 ? 16 : lda;
;   {int _b=t5*16;int _r,_c;g_stage_rc(_b,_r,_c);
;     oa0=n2 ? (unsigned)((n2*(_r&63)+(_r>>6))*1024+_c) : (unsigned)(_r*lda+_c); ob0=(unsigned)(_r*ldb+_c);}
;   STAGE(SB(0,0),Bt,ldb,0,0); STAGE(SA(0,0),A,lda,0,0);
;   STAGE(SB(0,1),Bt,ldb,G_HALF,0); STAGE(SA(0,1),A,lda,G_HALF,0);
;   if(wr==1)BAR;
; __device__ void job_retout_g(const P& p, int l, int job, HALF* sm) {
;     ...
;   {
;     IDS8_FRESH
;     FOR_BJ FOR_NN {
;       const int i = bj * 128 + wc * 32 + n * 16 + fr;
;       const float sc = expf(lgb * (float)(256 - i));
;       FOR_AI FOR_M4 { acc[ai][bj][m][n] *= sc; }
;     }
;   }
;   __syncthreads();
;   {
;     const HALF* Pp = (const HALF*)(ws + G_PP) + ((size_t)(cgi * 256) * 4 + h) * 256;
;     const HALF* VT = (const HALF*)(ws + G_VT) + (size_t)(h * 512 + nt2 * 256) * 8192 + cgi * 256;
;     gemm256(acc, VT, 8192, Pp, 1024, 256, sm);
.LBB0_485:
	s_or_b64 exec, exec, s[6:7]
	v_mov_b32_e32 v74, v155
	v_mov_b32_e32 v157, v155
	s_add_u32 s6, s2, s8
	v_bfe_i32 v73, v157, 27, 1
	v_lshlrev_b32_e32 v191, 4, v157
	v_lshrrev_b32_e32 v73, 22, v73
	v_add_u32_e32 v73, v191, v73
	v_and_b32_e32 v73, 0xfffffc00, v73
	s_addc_u32 s7, s3, s9
	v_ashrrev_i32_e32 v72, 31, v157
	v_sub_u32_e32 v73, v191, v73
	s_add_u32 s6, s6, s15
	v_lshrrev_b32_e32 v72, 26, v72
	v_lshrrev_b32_e32 v75, 4, v73
	s_addc_u32 s7, s7, 0
	v_add_u32_e32 v72, v157, v72
	v_bitop3_b32 v75, v75, v73, 32 bitop3:0x6c
	v_ashrrev_i32_e32 v73, 31, v73
	s_add_u32 s6, s6, 0x2aeb0000
	v_ashrrev_i32_e32 v72, 6, v72
	v_lshrrev_b32_e32 v73, 26, v73
	s_addc_u32 s7, s7, 0
	s_or_b32 s8, s15, s16
	v_lshlrev_b32_e32 v80, 3, v72
	v_add_u32_e32 v73, v75, v73
	s_lshl_b32 s8, s8, 14
	v_and_b32_e32 v80, -16, v80
	v_ashrrev_i32_e32 v73, 6, v73
	s_add_u32 s10, s2, s8
	v_add_u32_e32 v80, v73, v80
	v_mul_i32_i24_e32 v73, 64, v73
	s_addc_u32 s11, s3, 0
	s_lshl_b64 s[8:9], s[0:1], 1
	v_sub_u32_e32 v73, v75, v73
	s_add_u32 s1, s10, s8
	v_lshlrev_b32_e32 v72, 5, v72
	v_ashrrev_i16_sdwa v73, v174, sext(v73) dst_sel:DWORD dst_unused:UNUSED_PAD src0_sel:DWORD src1_sel:BYTE_0
	s_addc_u32 s9, s11, s9
	v_and_b32_e32 v72, 32, v72
	v_bfe_i32 v73, v73, 0, 16
	v_lshlrev_b32_e32 v75, 10, v80
	v_add_u32_e32 v189, s95, v191
	s_add_u32 s8, s1, 0x1deb0000
	v_add3_u32 v152, v72, v73, v75
	v_readfirstlane_b32 s1, v189
	v_add_u32_e32 v190, 0x2000, v189
	v_lshl_add_u64 v[164:165], v[152:153], 1, s[6:7]
	s_mov_b32 m0, s1
	s_mov_b64 s[6:7], 0x20000
	v_readfirstlane_b32 s1, v190
	s_waitcnt vmcnt(0)
	s_barrier
	global_load_lds_dwordx4 v[164:165], off
	v_lshl_add_u64 v[72:73], v[164:165], 0, s[6:7]
	s_mov_b32 m0, s1
	s_movk_i32 s1, 0x1c00
	global_load_lds_dwordx4 v[72:73], off
	v_mad_u64_u32 v[72:73], s[6:7], v80, s1, v[152:153]
	v_add_u32_e32 v187, 0, v191
	s_addc_u32 s9, s9, 0
	v_mov_b32_e32 v73, v153
	v_readfirstlane_b32 s1, v187
	v_add_u32_e32 v188, 0x2000, v187
	v_lshl_add_u64 v[160:161], v[72:73], 1, s[8:9]
	s_mov_b32 m0, s1
	s_mov_b64 s[6:7], 0x100000
	v_readfirstlane_b32 s1, v188
	v_add_u32_e32 v172, s28, v191
	global_load_lds_dwordx4 v[160:161], off
	v_lshl_add_u64 v[72:73], v[160:161], 0, s[6:7]
	s_mov_b32 m0, s1
	s_mov_b64 s[6:7], 0x40000
	v_readfirstlane_b32 s1, v172
	v_add_u32_e32 v186, 0x2000, v172
	global_load_lds_dwordx4 v[72:73], off
	v_lshl_add_u64 v[162:163], v[164:165], 0, s[6:7]
	s_mov_b32 m0, s1
	s_mov_b64 s[6:7], 0x60000
	v_readfirstlane_b32 s1, v186
	v_add_u32_e32 v159, 0x4000, v187
	global_load_lds_dwordx4 v[162:163], off
	v_lshl_add_u64 v[72:73], v[164:165], 0, s[6:7]
	s_mov_b32 m0, s1
	s_mov_b64 s[6:7], 0x200000
	v_readfirstlane_b32 s1, v159
	v_add_u32_e32 v170, 0x6000, v187
	global_load_lds_dwordx4 v[72:73], off
	v_lshl_add_u64 v[166:167], v[160:161], 0, s[6:7]
	s_mov_b32 m0, s1
	s_mov_b64 s[6:7], 0x300000
	v_readfirstlane_b32 s1, v170
	global_load_lds_dwordx4 v[166:167], off
	v_lshl_add_u64 v[72:73], v[160:161], 0, s[6:7]
	s_mov_b32 m0, s1
	s_movk_i32 s1, 0x60
	global_load_lds_dwordx4 v[72:73], off
	v_and_b32_e32 v72, 15, v74
	v_lshrrev_b32_e32 v73, 1, v74
	v_and_or_b32 v72, v73, s1, v72
	v_sub_u32_e32 v73, 0x100, v72
	v_cvt_f32_u32_e32 v73, v73
	v_ashrrev_i32_e32 v192, 8, v157
	v_mul_f32_e64 v73, -v158, v73
	v_mul_f32_e32 v74, 0x3fb8aa3b, v73
	v_fma_f32 v75, v73, s30, -v74
	v_rndne_f32_e32 v80, v74
	v_fmac_f32_e32 v75, 0x32a5705f, v73
	v_sub_f32_e32 v74, v74, v80
	v_add_f32_e32 v74, v74, v75
	v_exp_f32_e32 v74, v74
	v_cvt_i32_f32_e32 v75, v80
	v_cmp_ngt_f32_e32 vcc, s33, v73
	v_ldexp_f32 v74, v74, v75
	v_or_b32_e32 v75, 16, v72
	v_sub_u32_e32 v80, 0x100, v75
	v_cvt_f32_ubyte0_e32 v80, v80
	v_mul_f32_e64 v80, -v158, v80
	v_mul_f32_e32 v81, 0x3fb8aa3b, v80
	v_fma_f32 v82, v80, s30, -v81
	v_rndne_f32_e32 v83, v81
	v_fmac_f32_e32 v82, 0x32a5705f, v80
	v_sub_f32_e32 v81, v81, v83
	v_add_f32_e32 v81, v81, v82
	v_exp_f32_e32 v81, v81
	v_cvt_i32_f32_e32 v82, v83
	v_sub_u32_e32 v72, 0x80, v72
	v_cvt_f32_ubyte0_e32 v72, v72
	v_cndmask_b32_e32 v74, 0, v74, vcc
	v_cmp_nlt_f32_e32 vcc, s86, v73
	v_mul_f32_e64 v72, -v158, v72
	v_ldexp_f32 v73, v81, v82
	v_cndmask_b32_e32 v120, v181, v74, vcc
	v_mul_f32_e32 v74, 0x3fb8aa3b, v72
	v_fma_f32 v81, v72, s30, -v74
	v_rndne_f32_e32 v82, v74
	v_fmac_f32_e32 v81, 0x32a5705f, v72
	v_sub_f32_e32 v74, v74, v82
	v_add_f32_e32 v74, v74, v81
	v_exp_f32_e32 v74, v74
	v_cvt_i32_f32_e32 v81, v82
	v_cmp_ngt_f32_e32 vcc, s33, v80
	s_nop 1
	v_cndmask_b32_e32 v73, 0, v73, vcc
	v_cmp_nlt_f32_e32 vcc, s86, v80
	s_nop 1
	v_cndmask_b32_e32 v168, v181, v73, vcc
	v_ldexp_f32 v73, v74, v81
	v_sub_u32_e32 v74, 0x80, v75
	v_cvt_f32_ubyte0_e32 v74, v74
	v_mul_f32_e64 v74, -v158, v74
	v_mul_f32_e32 v75, 0x3fb8aa3b, v74
	v_fma_f32 v80, v74, s30, -v75
	v_rndne_f32_e32 v81, v75
	v_fmac_f32_e32 v80, 0x32a5705f, v74
	v_sub_f32_e32 v75, v75, v81
	v_add_f32_e32 v75, v75, v80
	v_exp_f32_e32 v75, v75
	v_cvt_i32_f32_e32 v80, v81
	v_cmp_ngt_f32_e32 vcc, s33, v72
	s_nop 1
	v_cndmask_b32_e32 v73, 0, v73, vcc
	v_cmp_nlt_f32_e32 vcc, s86, v72
	v_ldexp_f32 v72, v75, v80
	s_nop 0
	v_cndmask_b32_e32 v158, v181, v73, vcc
	v_cmp_ngt_f32_e32 vcc, s33, v74
	s_nop 1
	v_cndmask_b32_e32 v72, 0, v72, vcc
	v_cmp_nlt_f32_e32 vcc, s86, v74
	s_nop 1
	v_cndmask_b32_e32 v152, v181, v72, vcc
	v_cmp_eq_u32_e32 vcc, 1, v192
	s_and_saveexec_b64 s[6:7], vcc
	s_cbranch_execz .LBB0_487
	s_barrier

; DEV int opaque_tid512() { int t = threadIdx.x; asm volatile("" : "+v"(t)); return t; }
;   #define STAGE(P,BASE,LD,br,kt) do{ const HALF* _u=(BASE)+(long)(br)*(((&(LD))==&lda)?lda_u:(LD))+(long)(kt)*G_BK; \
;     for(int _i=0;_i<2;++_i){ \
;       __builtin_amdgcn_global_load_lds((const unsigned*)(_u+(long)_i*(((&(LD))==&lda)?stepa:stepb)+((&(LD))==&lda?oa0:ob0)), \
;         (unsigned*)((char*)(P)+t5*16+_i*8192),16,0,0);}}while(0)
;   #define BAR __builtin_amdgcn_s_barrier()
;     ...
;   const int t5=opaque_tid512();
;   const int wid=t5>>6,lane=t5&63,wr=wid>>2,wc=wid&3,fr=lane&15,fq=lane>>4;
;   h8 At[4][2],B0[2][2],B1[2][2];
;   const int nt=K/G_BK;
;   const int _ob=fr*64+fq*16, _sw=_ob^(((_ob>>9)&1)<<5);
;   const char* la=(const char*)shm+wr*8192+_sw;
;   const char* lb=(const char*)shm+65536+wc*4096+_sw;
;   unsigned oa0, ob0;
;   const int stepa = n2 ? 1024 : 64 * lda, stepb = 64 * ldb;
;   const int lda_u = n2 ? 16 : lda;
;   {int _b=t5*16;int _r,_c;g_stage_rc(_b,_r,_c);
;     oa0=n2 ? (unsigned)((n2*(_r&63)+(_r>>6))*1024+_c) : (unsigned)(_r*lda+_c); ob0=(unsigned)(_r*ldb+_c);}
;   STAGE(SB(0,0),Bt,ldb,0,0); STAGE(SA(0,0),A,lda,0,0);
;   STAGE(SB(0,1),Bt,ldb,G_HALF,0); STAGE(SA(0,1),A,lda,G_HALF,0);
;   if(wr==1)BAR;
; __device__ void job_ffn_in_g(const P& p, int job, HALF* sm) {
;     ...
;   const int ct2 = job % 22, rt = job / 22;
;   const HALF* Ap = (const HALF*)(ws + OFF_X16) + (size_t)(rt * 256) * 1024;
;   const HALF* Bp = (const HALF*)(ws + OFF_WFI) + (size_t)(ct2 * 256) * 1024;
;   f4 acc[2][2][4][2];
;   zero_acc256(acc);
;   asm volatile("s_waitcnt vmcnt(0)" ::: "memory");
;   __syncthreads();
;   gemm256(acc, Bp, 1024, Ap, 1024, 1024, sm);
.LBB0_613:
	v_readlane_b32 s8, v255, 39
	v_readlane_b32 s12, v255, 43
	v_readlane_b32 s13, v255, 44
	v_mov_b32_e32 v130, v155
	s_mov_b64 s[2:3], s[12:13]
	v_mov_b32_e32 v131, v155
	s_mul_hi_i32 s1, s0, 0x2e8ba2e9
	v_ashrrev_i32_e32 v0, 31, v131
	v_lshrrev_b32_e32 v0, 26, v0
	v_add_u32_e32 v0, v131, v0
	v_ashrrev_i32_e32 v4, 6, v0
	v_bfe_i32 v0, v131, 27, 1
	s_lshr_b32 s6, s1, 31
	s_ashr_i32 s1, s1, 2
	v_lshlrev_b32_e32 v5, 4, v131
	v_lshrrev_b32_e32 v0, 22, v0
	s_add_i32 s1, s1, s6
	v_add_u32_e32 v0, v5, v0
	s_mul_i32 s6, s1, 22
	v_and_b32_e32 v0, 0xfffffc00, v0
	s_sub_i32 s18, s0, s6
	s_lshl_b32 s0, s1, 8
	v_sub_u32_e32 v0, v5, v0
	v_readlane_b32 s9, v255, 40
	s_ashr_i32 s1, s0, 31
	v_lshrrev_b32_e32 v1, 4, v0
	s_lshl_b64 s[8:9], s[0:1], 11
	v_bitop3_b32 v1, v1, v0, 32 bitop3:0x6c
	v_ashrrev_i32_e32 v0, 31, v0
	s_add_u32 s1, s2, s8
	v_lshrrev_b32_e32 v0, 26, v0
	s_addc_u32 s6, s3, s9
	v_lshlrev_b32_e32 v2, 3, v4
	v_add_u32_e32 v0, v1, v0
	s_add_u32 s12, s1, 0x3eb0000
	v_and_b32_e32 v2, 0x3ffff0, v2
	v_ashrrev_i32_e32 v6, 6, v0
	s_addc_u32 s13, s6, 0
	s_lshl_b32 s6, s18, 8
	v_add_u32_e32 v0, v6, v2
	v_lshlrev_b32_e32 v2, 5, v4
	v_readlane_b32 s10, v255, 41
	v_readlane_b32 s11, v255, 42
	s_ashr_i32 s7, s6, 31
	v_and_b32_e32 v7, 32, v2
	v_mul_i32_i24_e32 v2, 64, v6
	s_lshl_b64 s[10:11], s[6:7], 11
	v_sub_u32_e32 v1, v1, v2
	s_add_u32 s1, s2, s10
	v_ashrrev_i16_sdwa v8, v174, sext(v1) dst_sel:DWORD dst_unused:UNUSED_PAD src0_sel:DWORD src1_sel:BYTE_0
	v_lshl_or_b32 v0, v0, 10, v7
	s_addc_u32 s7, s3, s11
	v_add_u32_sdwa v152, v0, sext(v8) dst_sel:DWORD dst_unused:UNUSED_PAD src0_sel:DWORD src1_sel:WORD_0
	v_add_u32_e32 v134, s95, v5
	v_readlane_b32 s14, v255, 45
	v_readlane_b32 s15, v255, 46
	s_add_u32 s6, s1, 0x2600000
	v_lshlrev_b64 v[2:3], 1, v[152:153]
	v_readfirstlane_b32 s1, v134
	v_add_u32_e32 v135, 0x2000, v134
	v_lshl_add_u64 v[0:1], s[12:13], 0, v[2:3]
	s_mov_b32 m0, s1
	s_mov_b64 s[14:15], 0x20000
	v_readfirstlane_b32 s1, v135
	v_add_u32_e32 v136, 0, v5
	s_addc_u32 s7, s7, 0
	s_waitcnt vmcnt(0)
	s_barrier
	global_load_lds_dwordx4 v[0:1], off
	v_lshl_add_u64 v[10:11], v[0:1], 0, s[14:15]
	s_mov_b32 m0, s1
	v_readfirstlane_b32 s1, v136
	v_add_u32_e32 v137, 0x2000, v136
	global_load_lds_dwordx4 v[10:11], off
	v_lshl_add_u64 v[2:3], s[6:7], 0, v[2:3]
	s_mov_b32 m0, s1
	v_readfirstlane_b32 s1, v137
	v_add_u32_e32 v138, s28, v5
	global_load_lds_dwordx4 v[2:3], off
	v_lshl_add_u64 v[10:11], v[2:3], 0, s[14:15]
	s_mov_b32 m0, s1
	s_mov_b64 s[14:15], 0x40000
	v_readfirstlane_b32 s1, v138
	v_add_u32_e32 v139, 0x2000, v138
	global_load_lds_dwordx4 v[10:11], off
	v_lshl_add_u64 v[10:11], v[0:1], 0, s[14:15]
	s_mov_b32 m0, s1
	s_mov_b64 s[20:21], 0x60000
	v_readfirstlane_b32 s1, v139
	v_add_u32_e32 v140, 0x4000, v136
	global_load_lds_dwordx4 v[10:11], off
	v_lshl_add_u64 v[10:11], v[0:1], 0, s[20:21]
	s_mov_b32 m0, s1
	v_readfirstlane_b32 s1, v140
	v_add_u32_e32 v141, 0x6000, v136
	global_load_lds_dwordx4 v[10:11], off
	v_lshl_add_u64 v[10:11], v[2:3], 0, s[14:15]
	s_mov_b32 m0, s1
	v_readfirstlane_b32 s1, v141
	global_load_lds_dwordx4 v[10:11], off
	v_lshl_add_u64 v[10:11], v[2:3], 0, s[20:21]
	s_mov_b32 m0, s1
	v_ashrrev_i32_e32 v9, 8, v131
	global_load_lds_dwordx4 v[10:11], off
	v_cmp_eq_u32_e32 vcc, 1, v9
	s_and_saveexec_b64 s[14:15], vcc
	s_cbranch_execz .LBB0_615
	s_barrier

; DEV int opaque_tid512() { int t = threadIdx.x; asm volatile("" : "+v"(t)); return t; }
;   #define STAGE(P,BASE,LD,br,kt) do{ const HALF* _u=(BASE)+(long)(br)*(((&(LD))==&lda)?lda_u:(LD))+(long)(kt)*G_BK; \
;     for(int _i=0;_i<2;++_i){ \
;       __builtin_amdgcn_global_load_lds((const unsigned*)(_u+(long)_i*(((&(LD))==&lda)?stepa:stepb)+((&(LD))==&lda?oa0:ob0)), \
;         (unsigned*)((char*)(P)+t5*16+_i*8192),16,0,0);}}while(0)
;   #define BAR __builtin_amdgcn_s_barrier()
;     ...
;   const int t5=opaque_tid512();
;   const int wid=t5>>6,lane=t5&63,wr=wid>>2,wc=wid&3,fr=lane&15,fq=lane>>4;
;   h8 At[4][2],B0[2][2],B1[2][2];
;   const int nt=K/G_BK;
;   const int _ob=fr*64+fq*16, _sw=_ob^(((_ob>>9)&1)<<5);
;   const char* la=(const char*)shm+wr*8192+_sw;
;   const char* lb=(const char*)shm+65536+wc*4096+_sw;
;   unsigned oa0, ob0;
;   const int stepa = n2 ? 1024 : 64 * lda, stepb = 64 * ldb;
;   const int lda_u = n2 ? 16 : lda;
;   {int _b=t5*16;int _r,_c;g_stage_rc(_b,_r,_c);
;     oa0=n2 ? (unsigned)((n2*(_r&63)+(_r>>6))*1024+_c) : (unsigned)(_r*lda+_c); ob0=(unsigned)(_r*ldb+_c);}
;   STAGE(SB(0,0),Bt,ldb,0,0); STAGE(SA(0,0),A,lda,0,0);
;   STAGE(SB(0,1),Bt,ldb,G_HALF,0); STAGE(SA(0,1),A,lda,G_HALF,0);
;   if(wr==1)BAR;
; template <int K>
; __device__ void job_resid_g(const P& p, const HALF* A, const HALF* Bt, int job, HALF* sm) {
;     ...
;   const int ct2 = job & 3, rt = job >> 2;
;   const HALF* Ap = A + (size_t)(rt * 256) * K;
;   const HALF* Bp = Bt + (size_t)(ct2 * 256) * K;
;   f4 acc[2][2][4][2];
;   zero_acc256(acc);
;   asm volatile("s_waitcnt vmcnt(0)" ::: "memory");
;   __syncthreads();
;   gemm256(acc, Ap, K, Bp, K, K, sm);
.LBB0_663:
	v_readlane_b32 s68, v255, 39
	v_readlane_b32 s72, v255, 43
	v_readlane_b32 s73, v255, 44
	v_mov_b32_e32 v130, v155
	s_mov_b64 s[2:3], s[72:73]
	v_mov_b32_e32 v131, v155
	s_lshl_b32 s0, s8, 6
	v_ashrrev_i32_e32 v0, 31, v131
	v_lshrrev_b32_e32 v0, 26, v0
	v_add_u32_e32 v0, v131, v0
	v_ashrrev_i32_e32 v4, 6, v0
	v_bfe_i32 v0, v131, 27, 1
	v_lshlrev_b32_e32 v5, 4, v131
	v_lshrrev_b32_e32 v0, 22, v0
	v_add_u32_e32 v0, v5, v0
	v_and_b32_e32 v0, 0xfffffc00, v0
	v_sub_u32_e32 v0, v5, v0
	v_lshrrev_b32_e32 v1, 4, v0
	v_bitop3_b32 v1, v1, v0, 32 bitop3:0x6c
	v_ashrrev_i32_e32 v0, 31, v0
	v_lshrrev_b32_e32 v0, 26, v0
	s_and_b32 s0, s0, 0xffffff00
	v_lshlrev_b32_e32 v2, 3, v4
	v_add_u32_e32 v0, v1, v0
	s_ashr_i32 s1, s0, 31
	s_mul_i32 s16, s0, 0x1600
	v_readlane_b32 s6, v254, 53
	v_and_b32_e32 v2, 0xfffff0, v2
	v_ashrrev_i32_e32 v7, 6, v0
	s_mul_hi_i32 s15, s0, 0x1600
	s_add_u32 s6, s6, s16
	v_readlane_b32 s7, v254, 54
	v_add_u32_e32 v0, v7, v2
	v_lshlrev_b32_e32 v2, 5, v4
	s_addc_u32 s7, s7, s15
	s_lshl_b32 s8, s8, 8
	v_and_b32_e32 v6, 32, v2
	v_mul_i32_i24_e32 v2, 64, v7
	s_movk_i32 s10, 0xb00
	s_and_b32 s14, s8, 0x300
	v_sub_u32_e32 v1, v1, v2
	v_mul_lo_u32 v0, v0, s10
	s_mul_i32 s17, s14, 0x1600
	v_readlane_b32 s8, v255, 13
	v_ashrrev_i16_sdwa v8, v174, sext(v1) dst_sel:DWORD dst_unused:UNUSED_PAD src0_sel:DWORD src1_sel:BYTE_0
	v_or_b32_e32 v0, v0, v6
	s_add_u32 s8, s8, s17
	v_readlane_b32 s9, v255, 14
	v_add_u32_sdwa v152, v0, sext(v8) dst_sel:DWORD dst_unused:UNUSED_PAD src0_sel:DWORD src1_sel:WORD_0
	v_add_u32_e32 v134, s95, v5
	s_addc_u32 s9, s9, 0
	v_lshlrev_b64 v[2:3], 1, v[152:153]
	v_readfirstlane_b32 s10, v134
	v_add_u32_e32 v135, 0x2000, v134
	v_lshl_add_u64 v[0:1], s[8:9], 0, v[2:3]
	s_mov_b32 m0, s10
	s_mov_b64 s[18:19], 0x58000
	v_readfirstlane_b32 s10, v135
	v_add_u32_e32 v136, 0, v5
	s_waitcnt vmcnt(0)
	s_barrier
	global_load_lds_dwordx4 v[0:1], off
	v_lshl_add_u64 v[10:11], v[0:1], 0, s[18:19]
	s_mov_b32 m0, s10
	v_readfirstlane_b32 s10, v136
	v_add_u32_e32 v137, 0x2000, v136
	global_load_lds_dwordx4 v[10:11], off
	v_lshl_add_u64 v[2:3], s[6:7], 0, v[2:3]
	s_mov_b32 m0, s10
	v_readfirstlane_b32 s10, v137
	v_add_u32_e32 v138, s28, v5
	global_load_lds_dwordx4 v[2:3], off
	v_lshl_add_u64 v[10:11], v[2:3], 0, s[18:19]
	s_mov_b32 m0, s10
	s_mov_b64 s[18:19], 0xb0000
	v_readfirstlane_b32 s10, v138
	v_add_u32_e32 v139, 0x2000, v138
	global_load_lds_dwordx4 v[10:11], off
	v_lshl_add_u64 v[10:11], v[0:1], 0, s[18:19]
	s_mov_b32 m0, s10
	s_mov_b64 s[20:21], 0x108000
	v_readfirstlane_b32 s10, v139
	v_add_u32_e32 v140, 0x4000, v136
	global_load_lds_dwordx4 v[10:11], off
	v_lshl_add_u64 v[10:11], v[0:1], 0, s[20:21]
	s_mov_b32 m0, s10
	v_readfirstlane_b32 s10, v140
	v_add_u32_e32 v141, 0x6000, v136
	global_load_lds_dwordx4 v[10:11], off
	v_lshl_add_u64 v[10:11], v[2:3], 0, s[18:19]
	s_mov_b32 m0, s10
	v_readfirstlane_b32 s10, v141
	global_load_lds_dwordx4 v[10:11], off
	v_lshl_add_u64 v[10:11], v[2:3], 0, s[20:21]
	s_mov_b32 m0, s10
	v_ashrrev_i32_e32 v9, 8, v131
	global_load_lds_dwordx4 v[10:11], off
	v_cmp_eq_u32_e32 vcc, 1, v9
	v_readlane_b32 s69, v255, 40
	v_readlane_b32 s70, v255, 41
	v_readlane_b32 s71, v255, 42
	v_readlane_b32 s74, v255, 45
	v_readlane_b32 s75, v255, 46
	s_and_saveexec_b64 s[10:11], vcc
	s_cbranch_execz .LBB0_665
	s_barrier
